# final LayerNorm rows assigned to the XCD whose workgroups wrote them in the output projection (L2-resident out rows)
# baseline (speedup 1.0000x reference)
.LBB0_745:
	s_or_b64 exec, exec, s[0:1]
	s_mov_b64 s[4:5], s[88:89]
	s_waitcnt lgkmcnt(0)
	s_barrier
	s_cmpk_lg_u32 s56, 0x100
	s_cbranch_scc1 .Llo_generic
	s_load_dwordx2 s[6:7], s[4:5], 0xa0
	s_load_dwordx4 s[40:43], s[4:5], 0x90
	v_mbcnt_lo_u32_b32 v0, -1, 0
	v_mbcnt_hi_u32_b32 v0, -1, v0
	v_lshlrev_b32_e32 v1, 4, v0
	s_lshr_b32 s0, s29, 6
	s_lshl_b32 s96, s92, 24
	s_lshl_b64 s[8:9], s[96:97], 2
	v_mov_b32_e32 v2, 0x3a800000
	v_mov_b32_e32 v4, 0x3727c5ac
	s_waitcnt lgkmcnt(0)
	s_add_u32 s4, s6, s8
	s_addc_u32 s5, s7, s9
	s_cmp_eq_u32 s92, 2
	s_cbranch_scc1 .Llo_even
	s_cmp_lt_u32 s86, 64
	s_cbranch_scc1 .Llo_small
	s_sub_u32 s1, s86, 64
	s_lshr_b32 s1, s1, 3
	s_mul_i32 s1, s1, 80
	s_mul_i32 s0, s0, 10
	s_add_i32 s0, s0, s1
	s_add_i32 s0, s0, 128
	s_and_b32 s1, s86, 7
	s_lshl_b32 s1, s1, 11
	s_add_i32 s0, s0, s1
	s_lshl_b32 s0, s0, 12
	s_add_u32 s4, s4, s0
	s_addc_u32 s5, s5, 0
	global_load_dwordx4 v[40:43], v1, s[4:5]
	global_load_dwordx4 v[44:47], v1, s[4:5] offset:1024
	global_load_dwordx4 v[48:51], v1, s[4:5] offset:2048
	global_load_dwordx4 v[52:55], v1, s[4:5] offset:3072
	global_load_dwordx4 v[8:11], v1, s[40:41]
	global_load_dwordx4 v[12:15], v1, s[40:41] offset:1024
	global_load_dwordx4 v[16:19], v1, s[40:41] offset:2048
	global_load_dwordx4 v[20:23], v1, s[40:41] offset:3072
	global_load_dwordx4 v[24:27], v1, s[42:43]
	global_load_dwordx4 v[28:31], v1, s[42:43] offset:1024
	global_load_dwordx4 v[32:35], v1, s[42:43] offset:2048
	global_load_dwordx4 v[36:39], v1, s[42:43] offset:3072
	v_add_u32_e32 v170, 0x1000, v1
	global_load_dwordx4 v[56:59], v170, s[4:5]
	global_load_dwordx4 v[60:63], v170, s[4:5] offset:1024
	global_load_dwordx4 v[64:67], v170, s[4:5] offset:2048
	global_load_dwordx4 v[68:71], v170, s[4:5] offset:3072
	v_add_u32_e32 v170, 0x2000, v1
	global_load_dwordx4 v[72:75], v170, s[4:5]
	global_load_dwordx4 v[76:79], v170, s[4:5] offset:1024
	global_load_dwordx4 v[80:83], v170, s[4:5] offset:2048
	global_load_dwordx4 v[84:87], v170, s[4:5] offset:3072
	v_add_u32_e32 v170, 0x3000, v1
	global_load_dwordx4 v[88:91], v170, s[4:5]
	global_load_dwordx4 v[92:95], v170, s[4:5] offset:1024
	global_load_dwordx4 v[96:99], v170, s[4:5] offset:2048
	global_load_dwordx4 v[100:103], v170, s[4:5] offset:3072
	v_add_u32_e32 v170, 0x4000, v1
	global_load_dwordx4 v[104:107], v170, s[4:5]
	global_load_dwordx4 v[108:111], v170, s[4:5] offset:1024
	global_load_dwordx4 v[112:115], v170, s[4:5] offset:2048
	global_load_dwordx4 v[116:119], v170, s[4:5] offset:3072
	v_add_u32_e32 v170, 0x5000, v1
	global_load_dwordx4 v[120:123], v170, s[4:5]
	global_load_dwordx4 v[124:127], v170, s[4:5] offset:1024
	global_load_dwordx4 v[128:131], v170, s[4:5] offset:2048
	global_load_dwordx4 v[132:135], v170, s[4:5] offset:3072
	v_add_u32_e32 v170, 0x6000, v1
	global_load_dwordx4 v[136:139], v170, s[4:5]
	global_load_dwordx4 v[140:143], v170, s[4:5] offset:1024
	global_load_dwordx4 v[144:147], v170, s[4:5] offset:2048
	global_load_dwordx4 v[148:151], v170, s[4:5] offset:3072
	v_add_u32_e32 v170, 0x7000, v1
	global_load_dwordx4 v[152:155], v170, s[4:5]
	global_load_dwordx4 v[156:159], v170, s[4:5] offset:1024
	global_load_dwordx4 v[160:163], v170, s[4:5] offset:2048
	global_load_dwordx4 v[164:167], v170, s[4:5] offset:3072
	s_waitcnt vmcnt(36)
	v_add_f32_e32 v180, v40, v41
	v_add_f32_e32 v181, v44, v45
	v_add_f32_e32 v182, v48, v49
	v_add_f32_e32 v183, v52, v53
	v_add_f32_e32 v180, v180, v42
	v_add_f32_e32 v181, v181, v46
	v_add_f32_e32 v182, v182, v50
	v_add_f32_e32 v183, v183, v54
	v_add_f32_e32 v180, v180, v43
	v_add_f32_e32 v181, v181, v47
	v_add_f32_e32 v182, v182, v51
	v_add_f32_e32 v183, v183, v55
	v_add_f32_e32 v180, v180, v181
	v_add_f32_e32 v182, v182, v183
	v_add_f32_e32 v180, v180, v182
	s_nop 1
	v_add_f32_dpp v180, v180, v180 quad_perm:[1,0,3,2] row_mask:0xf bank_mask:0xf
	s_nop 1
	v_add_f32_dpp v180, v180, v180 quad_perm:[2,3,0,1] row_mask:0xf bank_mask:0xf
	s_nop 1
	v_add_f32_dpp v180, v180, v180 row_half_mirror row_mask:0xf bank_mask:0xf
	s_nop 1
	v_add_f32_dpp v180, v180, v180 row_mirror row_mask:0xf bank_mask:0xf
	s_nop 1
	v_add_f32_dpp v180, v180, v180 row_bcast:15 row_mask:0xa bank_mask:0xf
	s_nop 1
	v_add_f32_dpp v180, v180, v180 row_bcast:31 row_mask:0xc bank_mask:0xf
	s_nop 0
	v_readlane_b32 s20, v180, 63
	s_nop 1
	v_mul_f32_e32 v184, s20, v2
	v_sub_f32_e32 v40, v40, v184
	v_sub_f32_e32 v41, v41, v184
	v_sub_f32_e32 v42, v42, v184
	v_sub_f32_e32 v43, v43, v184
	v_sub_f32_e32 v44, v44, v184
	v_sub_f32_e32 v45, v45, v184
	v_sub_f32_e32 v46, v46, v184
	v_sub_f32_e32 v47, v47, v184
	v_sub_f32_e32 v48, v48, v184
	v_sub_f32_e32 v49, v49, v184
	v_sub_f32_e32 v50, v50, v184
	v_sub_f32_e32 v51, v51, v184
	v_sub_f32_e32 v52, v52, v184
	v_sub_f32_e32 v53, v53, v184
	v_sub_f32_e32 v54, v54, v184
	v_sub_f32_e32 v55, v55, v184
	v_mul_f32_e32 v180, v40, v40
	v_mul_f32_e32 v181, v44, v44
	v_mul_f32_e32 v182, v48, v48
	v_mul_f32_e32 v183, v52, v52
	v_fmac_f32_e32 v180, v41, v41
	v_fmac_f32_e32 v181, v45, v45
	v_fmac_f32_e32 v182, v49, v49
	v_fmac_f32_e32 v183, v53, v53
	v_fmac_f32_e32 v180, v42, v42
	v_fmac_f32_e32 v181, v46, v46
	v_fmac_f32_e32 v182, v50, v50
	v_fmac_f32_e32 v183, v54, v54
	v_fmac_f32_e32 v180, v43, v43
	v_fmac_f32_e32 v181, v47, v47
	v_fmac_f32_e32 v182, v51, v51
	v_fmac_f32_e32 v183, v55, v55
	v_add_f32_e32 v180, v180, v181
	v_add_f32_e32 v182, v182, v183
	v_add_f32_e32 v180, v180, v182
	s_nop 1
	v_add_f32_dpp v180, v180, v180 quad_perm:[1,0,3,2] row_mask:0xf bank_mask:0xf
	s_nop 1
	v_add_f32_dpp v180, v180, v180 quad_perm:[2,3,0,1] row_mask:0xf bank_mask:0xf
	s_nop 1
	v_add_f32_dpp v180, v180, v180 row_half_mirror row_mask:0xf bank_mask:0xf
	s_nop 1
	v_add_f32_dpp v180, v180, v180 row_mirror row_mask:0xf bank_mask:0xf
	s_nop 1
	v_add_f32_dpp v180, v180, v180 row_bcast:15 row_mask:0xa bank_mask:0xf
	s_nop 1
	v_add_f32_dpp v180, v180, v180 row_bcast:31 row_mask:0xc bank_mask:0xf
	s_nop 0
	v_readlane_b32 s20, v180, 63
	s_nop 1
	v_mov_b32_e32 v185, s20
	v_fma_f32 v185, v185, v2, v4
	v_rsq_f32_e32 v185, v185
	s_nop 0
	v_mul_f32_e32 v40, v40, v185
	v_mul_f32_e32 v41, v41, v185
	v_mul_f32_e32 v42, v42, v185
	v_mul_f32_e32 v43, v43, v185
	v_mul_f32_e32 v44, v44, v185
	v_mul_f32_e32 v45, v45, v185
	v_mul_f32_e32 v46, v46, v185
	v_mul_f32_e32 v47, v47, v185
	v_mul_f32_e32 v48, v48, v185
	v_mul_f32_e32 v49, v49, v185
	v_mul_f32_e32 v50, v50, v185
	v_mul_f32_e32 v51, v51, v185
	v_mul_f32_e32 v52, v52, v185
	v_mul_f32_e32 v53, v53, v185
	v_mul_f32_e32 v54, v54, v185
	v_mul_f32_e32 v55, v55, v185
	s_waitcnt vmcnt(28)
	v_fma_f32 v40, v40, v8, v24
	v_fma_f32 v41, v41, v9, v25
	v_fma_f32 v42, v42, v10, v26
	v_fma_f32 v43, v43, v11, v27
	v_fma_f32 v44, v44, v12, v28
	v_fma_f32 v45, v45, v13, v29
	v_fma_f32 v46, v46, v14, v30
	v_fma_f32 v47, v47, v15, v31
	v_fma_f32 v48, v48, v16, v32
	v_fma_f32 v49, v49, v17, v33
	v_fma_f32 v50, v50, v18, v34
	v_fma_f32 v51, v51, v19, v35
	v_fma_f32 v52, v52, v20, v36
	v_fma_f32 v53, v53, v21, v37
	v_fma_f32 v54, v54, v22, v38
	v_fma_f32 v55, v55, v23, v39
	global_store_dwordx4 v1, v[40:43], s[4:5]
	global_store_dwordx4 v1, v[44:47], s[4:5] offset:1024
	global_store_dwordx4 v1, v[48:51], s[4:5] offset:2048
	global_store_dwordx4 v1, v[52:55], s[4:5] offset:3072
	s_nop 1
	v_add_u32_e32 v170, 0x8000, v1
	global_load_dwordx4 v[40:43], v170, s[4:5]
	global_load_dwordx4 v[44:47], v170, s[4:5] offset:1024
	global_load_dwordx4 v[48:51], v170, s[4:5] offset:2048
	global_load_dwordx4 v[52:55], v170, s[4:5] offset:3072
	s_waitcnt vmcnt(32)
	v_add_f32_e32 v180, v56, v57
	v_add_f32_e32 v181, v60, v61
	v_add_f32_e32 v182, v64, v65
	v_add_f32_e32 v183, v68, v69
	v_add_f32_e32 v180, v180, v58
	v_add_f32_e32 v181, v181, v62
	v_add_f32_e32 v182, v182, v66
	v_add_f32_e32 v183, v183, v70
	v_add_f32_e32 v180, v180, v59
	v_add_f32_e32 v181, v181, v63
	v_add_f32_e32 v182, v182, v67
	v_add_f32_e32 v183, v183, v71
	v_add_f32_e32 v180, v180, v181
	v_add_f32_e32 v182, v182, v183
	v_add_f32_e32 v180, v180, v182
	s_nop 1
	v_add_f32_dpp v180, v180, v180 quad_perm:[1,0,3,2] row_mask:0xf bank_mask:0xf
	s_nop 1
	v_add_f32_dpp v180, v180, v180 quad_perm:[2,3,0,1] row_mask:0xf bank_mask:0xf
	s_nop 1
	v_add_f32_dpp v180, v180, v180 row_half_mirror row_mask:0xf bank_mask:0xf
	s_nop 1
	v_add_f32_dpp v180, v180, v180 row_mirror row_mask:0xf bank_mask:0xf
	s_nop 1
	v_add_f32_dpp v180, v180, v180 row_bcast:15 row_mask:0xa bank_mask:0xf
	s_nop 1
	v_add_f32_dpp v180, v180, v180 row_bcast:31 row_mask:0xc bank_mask:0xf
	s_nop 0
	v_readlane_b32 s20, v180, 63
	s_nop 1
	v_mul_f32_e32 v184, s20, v2
	v_sub_f32_e32 v56, v56, v184
	v_sub_f32_e32 v57, v57, v184
	v_sub_f32_e32 v58, v58, v184
	v_sub_f32_e32 v59, v59, v184
	v_sub_f32_e32 v60, v60, v184
	v_sub_f32_e32 v61, v61, v184
	v_sub_f32_e32 v62, v62, v184
	v_sub_f32_e32 v63, v63, v184
	v_sub_f32_e32 v64, v64, v184
	v_sub_f32_e32 v65, v65, v184
	v_sub_f32_e32 v66, v66, v184
	v_sub_f32_e32 v67, v67, v184
	v_sub_f32_e32 v68, v68, v184
	v_sub_f32_e32 v69, v69, v184
	v_sub_f32_e32 v70, v70, v184
	v_sub_f32_e32 v71, v71, v184
	v_mul_f32_e32 v180, v56, v56
	v_mul_f32_e32 v181, v60, v60
	v_mul_f32_e32 v182, v64, v64
	v_mul_f32_e32 v183, v68, v68
	v_fmac_f32_e32 v180, v57, v57
	v_fmac_f32_e32 v181, v61, v61
	v_fmac_f32_e32 v182, v65, v65
	v_fmac_f32_e32 v183, v69, v69
	v_fmac_f32_e32 v180, v58, v58
	v_fmac_f32_e32 v181, v62, v62
	v_fmac_f32_e32 v182, v66, v66
	v_fmac_f32_e32 v183, v70, v70
	v_fmac_f32_e32 v180, v59, v59
	v_fmac_f32_e32 v181, v63, v63
	v_fmac_f32_e32 v182, v67, v67
	v_fmac_f32_e32 v183, v71, v71
	v_add_f32_e32 v180, v180, v181
	v_add_f32_e32 v182, v182, v183
	v_add_f32_e32 v180, v180, v182
	s_nop 1
	v_add_f32_dpp v180, v180, v180 quad_perm:[1,0,3,2] row_mask:0xf bank_mask:0xf
	s_nop 1
	v_add_f32_dpp v180, v180, v180 quad_perm:[2,3,0,1] row_mask:0xf bank_mask:0xf
	s_nop 1
	v_add_f32_dpp v180, v180, v180 row_half_mirror row_mask:0xf bank_mask:0xf
	s_nop 1
	v_add_f32_dpp v180, v180, v180 row_mirror row_mask:0xf bank_mask:0xf
	s_nop 1
	v_add_f32_dpp v180, v180, v180 row_bcast:15 row_mask:0xa bank_mask:0xf
	s_nop 1
	v_add_f32_dpp v180, v180, v180 row_bcast:31 row_mask:0xc bank_mask:0xf
	s_nop 0
	v_readlane_b32 s20, v180, 63
	s_nop 1
	v_mov_b32_e32 v185, s20
	v_fma_f32 v185, v185, v2, v4
	v_rsq_f32_e32 v185, v185
	s_nop 0
	v_mul_f32_e32 v56, v56, v185
	v_mul_f32_e32 v57, v57, v185
	v_mul_f32_e32 v58, v58, v185
	v_mul_f32_e32 v59, v59, v185
	v_mul_f32_e32 v60, v60, v185
	v_mul_f32_e32 v61, v61, v185
	v_mul_f32_e32 v62, v62, v185
	v_mul_f32_e32 v63, v63, v185
	v_mul_f32_e32 v64, v64, v185
	v_mul_f32_e32 v65, v65, v185
	v_mul_f32_e32 v66, v66, v185
	v_mul_f32_e32 v67, v67, v185
	v_mul_f32_e32 v68, v68, v185
	v_mul_f32_e32 v69, v69, v185
	v_mul_f32_e32 v70, v70, v185
	v_mul_f32_e32 v71, v71, v185
	v_fma_f32 v56, v56, v8, v24
	v_fma_f32 v57, v57, v9, v25
	v_fma_f32 v58, v58, v10, v26
	v_fma_f32 v59, v59, v11, v27
	v_fma_f32 v60, v60, v12, v28
	v_fma_f32 v61, v61, v13, v29
	v_fma_f32 v62, v62, v14, v30
	v_fma_f32 v63, v63, v15, v31
	v_fma_f32 v64, v64, v16, v32
	v_fma_f32 v65, v65, v17, v33
	v_fma_f32 v66, v66, v18, v34
	v_fma_f32 v67, v67, v19, v35
	v_fma_f32 v68, v68, v20, v36
	v_fma_f32 v69, v69, v21, v37
	v_fma_f32 v70, v70, v22, v38
	v_fma_f32 v71, v71, v23, v39
	v_add_u32_e32 v171, 0x1000, v1
	global_store_dwordx4 v171, v[56:59], s[4:5]
	global_store_dwordx4 v171, v[60:63], s[4:5] offset:1024
	global_store_dwordx4 v171, v[64:67], s[4:5] offset:2048
	global_store_dwordx4 v171, v[68:71], s[4:5] offset:3072
	s_nop 1
	v_add_u32_e32 v170, 0x9000, v1
	global_load_dwordx4 v[56:59], v170, s[4:5]
	global_load_dwordx4 v[60:63], v170, s[4:5] offset:1024
	global_load_dwordx4 v[64:67], v170, s[4:5] offset:2048
	global_load_dwordx4 v[68:71], v170, s[4:5] offset:3072
	s_waitcnt vmcnt(36)
	v_add_f32_e32 v180, v72, v73
	v_add_f32_e32 v181, v76, v77
	v_add_f32_e32 v182, v80, v81
	v_add_f32_e32 v183, v84, v85
	v_add_f32_e32 v180, v180, v74
	v_add_f32_e32 v181, v181, v78
	v_add_f32_e32 v182, v182, v82
	v_add_f32_e32 v183, v183, v86
	v_add_f32_e32 v180, v180, v75
	v_add_f32_e32 v181, v181, v79
	v_add_f32_e32 v182, v182, v83
	v_add_f32_e32 v183, v183, v87
	v_add_f32_e32 v180, v180, v181
	v_add_f32_e32 v182, v182, v183
	v_add_f32_e32 v180, v180, v182
	s_nop 1
	v_add_f32_dpp v180, v180, v180 quad_perm:[1,0,3,2] row_mask:0xf bank_mask:0xf
	s_nop 1
	v_add_f32_dpp v180, v180, v180 quad_perm:[2,3,0,1] row_mask:0xf bank_mask:0xf
	s_nop 1
	v_add_f32_dpp v180, v180, v180 row_half_mirror row_mask:0xf bank_mask:0xf
	s_nop 1
	v_add_f32_dpp v180, v180, v180 row_mirror row_mask:0xf bank_mask:0xf
	s_nop 1
	v_add_f32_dpp v180, v180, v180 row_bcast:15 row_mask:0xa bank_mask:0xf
	s_nop 1
	v_add_f32_dpp v180, v180, v180 row_bcast:31 row_mask:0xc bank_mask:0xf
	s_nop 0
	v_readlane_b32 s20, v180, 63
	s_nop 1
	v_mul_f32_e32 v184, s20, v2
	v_sub_f32_e32 v72, v72, v184
	v_sub_f32_e32 v73, v73, v184
	v_sub_f32_e32 v74, v74, v184
	v_sub_f32_e32 v75, v75, v184
	v_sub_f32_e32 v76, v76, v184
	v_sub_f32_e32 v77, v77, v184
	v_sub_f32_e32 v78, v78, v184
	v_sub_f32_e32 v79, v79, v184
	v_sub_f32_e32 v80, v80, v184
	v_sub_f32_e32 v81, v81, v184
	v_sub_f32_e32 v82, v82, v184
	v_sub_f32_e32 v83, v83, v184
	v_sub_f32_e32 v84, v84, v184
	v_sub_f32_e32 v85, v85, v184
	v_sub_f32_e32 v86, v86, v184
	v_sub_f32_e32 v87, v87, v184
	v_mul_f32_e32 v180, v72, v72
	v_mul_f32_e32 v181, v76, v76
	v_mul_f32_e32 v182, v80, v80
	v_mul_f32_e32 v183, v84, v84
	v_fmac_f32_e32 v180, v73, v73
	v_fmac_f32_e32 v181, v77, v77
	v_fmac_f32_e32 v182, v81, v81
	v_fmac_f32_e32 v183, v85, v85
	v_fmac_f32_e32 v180, v74, v74
	v_fmac_f32_e32 v181, v78, v78
	v_fmac_f32_e32 v182, v82, v82
	v_fmac_f32_e32 v183, v86, v86
	v_fmac_f32_e32 v180, v75, v75
	v_fmac_f32_e32 v181, v79, v79
	v_fmac_f32_e32 v182, v83, v83
	v_fmac_f32_e32 v183, v87, v87
	v_add_f32_e32 v180, v180, v181
	v_add_f32_e32 v182, v182, v183
	v_add_f32_e32 v180, v180, v182
	s_nop 1
	v_add_f32_dpp v180, v180, v180 quad_perm:[1,0,3,2] row_mask:0xf bank_mask:0xf
	s_nop 1
	v_add_f32_dpp v180, v180, v180 quad_perm:[2,3,0,1] row_mask:0xf bank_mask:0xf
	s_nop 1
	v_add_f32_dpp v180, v180, v180 row_half_mirror row_mask:0xf bank_mask:0xf
	s_nop 1
	v_add_f32_dpp v180, v180, v180 row_mirror row_mask:0xf bank_mask:0xf
	s_nop 1
	v_add_f32_dpp v180, v180, v180 row_bcast:15 row_mask:0xa bank_mask:0xf
	s_nop 1
	v_add_f32_dpp v180, v180, v180 row_bcast:31 row_mask:0xc bank_mask:0xf
	s_nop 0
	v_readlane_b32 s20, v180, 63
	s_nop 1
	v_mov_b32_e32 v185, s20
	v_fma_f32 v185, v185, v2, v4
	v_rsq_f32_e32 v185, v185
	s_nop 0
	v_mul_f32_e32 v72, v72, v185
	v_mul_f32_e32 v73, v73, v185
	v_mul_f32_e32 v74, v74, v185
	v_mul_f32_e32 v75, v75, v185
	v_mul_f32_e32 v76, v76, v185
	v_mul_f32_e32 v77, v77, v185
	v_mul_f32_e32 v78, v78, v185
	v_mul_f32_e32 v79, v79, v185
	v_mul_f32_e32 v80, v80, v185
	v_mul_f32_e32 v81, v81, v185
	v_mul_f32_e32 v82, v82, v185
	v_mul_f32_e32 v83, v83, v185
	v_mul_f32_e32 v84, v84, v185
	v_mul_f32_e32 v85, v85, v185
	v_mul_f32_e32 v86, v86, v185
	v_mul_f32_e32 v87, v87, v185
	v_fma_f32 v72, v72, v8, v24
	v_fma_f32 v73, v73, v9, v25
	v_fma_f32 v74, v74, v10, v26
	v_fma_f32 v75, v75, v11, v27
	v_fma_f32 v76, v76, v12, v28
	v_fma_f32 v77, v77, v13, v29
	v_fma_f32 v78, v78, v14, v30
	v_fma_f32 v79, v79, v15, v31
	v_fma_f32 v80, v80, v16, v32
	v_fma_f32 v81, v81, v17, v33
	v_fma_f32 v82, v82, v18, v34
	v_fma_f32 v83, v83, v19, v35
	v_fma_f32 v84, v84, v20, v36
	v_fma_f32 v85, v85, v21, v37
	v_fma_f32 v86, v86, v22, v38
	v_fma_f32 v87, v87, v23, v39
	v_add_u32_e32 v171, 0x2000, v1
	global_store_dwordx4 v171, v[72:75], s[4:5]
	global_store_dwordx4 v171, v[76:79], s[4:5] offset:1024
	global_store_dwordx4 v171, v[80:83], s[4:5] offset:2048
	global_store_dwordx4 v171, v[84:87], s[4:5] offset:3072
	s_waitcnt vmcnt(36)
	v_add_f32_e32 v180, v88, v89
	v_add_f32_e32 v181, v92, v93
	v_add_f32_e32 v182, v96, v97
	v_add_f32_e32 v183, v100, v101
	v_add_f32_e32 v180, v180, v90
	v_add_f32_e32 v181, v181, v94
	v_add_f32_e32 v182, v182, v98
	v_add_f32_e32 v183, v183, v102
	v_add_f32_e32 v180, v180, v91
	v_add_f32_e32 v181, v181, v95
	v_add_f32_e32 v182, v182, v99
	v_add_f32_e32 v183, v183, v103
	v_add_f32_e32 v180, v180, v181
	v_add_f32_e32 v182, v182, v183
	v_add_f32_e32 v180, v180, v182
	s_nop 1
	v_add_f32_dpp v180, v180, v180 quad_perm:[1,0,3,2] row_mask:0xf bank_mask:0xf
	s_nop 1
	v_add_f32_dpp v180, v180, v180 quad_perm:[2,3,0,1] row_mask:0xf bank_mask:0xf
	s_nop 1
	v_add_f32_dpp v180, v180, v180 row_half_mirror row_mask:0xf bank_mask:0xf
	s_nop 1
	v_add_f32_dpp v180, v180, v180 row_mirror row_mask:0xf bank_mask:0xf
	s_nop 1
	v_add_f32_dpp v180, v180, v180 row_bcast:15 row_mask:0xa bank_mask:0xf
	s_nop 1
	v_add_f32_dpp v180, v180, v180 row_bcast:31 row_mask:0xc bank_mask:0xf
	s_nop 0
	v_readlane_b32 s20, v180, 63
	s_nop 1
	v_mul_f32_e32 v184, s20, v2
	v_sub_f32_e32 v88, v88, v184
	v_sub_f32_e32 v89, v89, v184
	v_sub_f32_e32 v90, v90, v184
	v_sub_f32_e32 v91, v91, v184
	v_sub_f32_e32 v92, v92, v184
	v_sub_f32_e32 v93, v93, v184
	v_sub_f32_e32 v94, v94, v184
	v_sub_f32_e32 v95, v95, v184
	v_sub_f32_e32 v96, v96, v184
	v_sub_f32_e32 v97, v97, v184
	v_sub_f32_e32 v98, v98, v184
	v_sub_f32_e32 v99, v99, v184
	v_sub_f32_e32 v100, v100, v184
	v_sub_f32_e32 v101, v101, v184
	v_sub_f32_e32 v102, v102, v184
	v_sub_f32_e32 v103, v103, v184
	v_mul_f32_e32 v180, v88, v88
	v_mul_f32_e32 v181, v92, v92
	v_mul_f32_e32 v182, v96, v96
	v_mul_f32_e32 v183, v100, v100
	v_fmac_f32_e32 v180, v89, v89
	v_fmac_f32_e32 v181, v93, v93
	v_fmac_f32_e32 v182, v97, v97
	v_fmac_f32_e32 v183, v101, v101
	v_fmac_f32_e32 v180, v90, v90
	v_fmac_f32_e32 v181, v94, v94
	v_fmac_f32_e32 v182, v98, v98
	v_fmac_f32_e32 v183, v102, v102
	v_fmac_f32_e32 v180, v91, v91
	v_fmac_f32_e32 v181, v95, v95
	v_fmac_f32_e32 v182, v99, v99
	v_fmac_f32_e32 v183, v103, v103
	v_add_f32_e32 v180, v180, v181
	v_add_f32_e32 v182, v182, v183
	v_add_f32_e32 v180, v180, v182
	s_nop 1
	v_add_f32_dpp v180, v180, v180 quad_perm:[1,0,3,2] row_mask:0xf bank_mask:0xf
	s_nop 1
	v_add_f32_dpp v180, v180, v180 quad_perm:[2,3,0,1] row_mask:0xf bank_mask:0xf
	s_nop 1
	v_add_f32_dpp v180, v180, v180 row_half_mirror row_mask:0xf bank_mask:0xf
	s_nop 1
	v_add_f32_dpp v180, v180, v180 row_mirror row_mask:0xf bank_mask:0xf
	s_nop 1
	v_add_f32_dpp v180, v180, v180 row_bcast:15 row_mask:0xa bank_mask:0xf
	s_nop 1
	v_add_f32_dpp v180, v180, v180 row_bcast:31 row_mask:0xc bank_mask:0xf
	s_nop 0
	v_readlane_b32 s20, v180, 63
	s_nop 1
	v_mov_b32_e32 v185, s20
	v_fma_f32 v185, v185, v2, v4
	v_rsq_f32_e32 v185, v185
	s_nop 0
	v_mul_f32_e32 v88, v88, v185
	v_mul_f32_e32 v89, v89, v185
	v_mul_f32_e32 v90, v90, v185
	v_mul_f32_e32 v91, v91, v185
	v_mul_f32_e32 v92, v92, v185
	v_mul_f32_e32 v93, v93, v185
	v_mul_f32_e32 v94, v94, v185
	v_mul_f32_e32 v95, v95, v185
	v_mul_f32_e32 v96, v96, v185
	v_mul_f32_e32 v97, v97, v185
	v_mul_f32_e32 v98, v98, v185
	v_mul_f32_e32 v99, v99, v185
	v_mul_f32_e32 v100, v100, v185
	v_mul_f32_e32 v101, v101, v185
	v_mul_f32_e32 v102, v102, v185
	v_mul_f32_e32 v103, v103, v185
	v_fma_f32 v88, v88, v8, v24
	v_fma_f32 v89, v89, v9, v25
	v_fma_f32 v90, v90, v10, v26
	v_fma_f32 v91, v91, v11, v27
	v_fma_f32 v92, v92, v12, v28
	v_fma_f32 v93, v93, v13, v29
	v_fma_f32 v94, v94, v14, v30
	v_fma_f32 v95, v95, v15, v31
	v_fma_f32 v96, v96, v16, v32
	v_fma_f32 v97, v97, v17, v33
	v_fma_f32 v98, v98, v18, v34
	v_fma_f32 v99, v99, v19, v35
	v_fma_f32 v100, v100, v20, v36
	v_fma_f32 v101, v101, v21, v37
	v_fma_f32 v102, v102, v22, v38
	v_fma_f32 v103, v103, v23, v39
	v_add_u32_e32 v171, 0x3000, v1
	global_store_dwordx4 v171, v[88:91], s[4:5]
	global_store_dwordx4 v171, v[92:95], s[4:5] offset:1024
	global_store_dwordx4 v171, v[96:99], s[4:5] offset:2048
	global_store_dwordx4 v171, v[100:103], s[4:5] offset:3072
	s_waitcnt vmcnt(36)
	v_add_f32_e32 v180, v104, v105
	v_add_f32_e32 v181, v108, v109
	v_add_f32_e32 v182, v112, v113
	v_add_f32_e32 v183, v116, v117
	v_add_f32_e32 v180, v180, v106
	v_add_f32_e32 v181, v181, v110
	v_add_f32_e32 v182, v182, v114
	v_add_f32_e32 v183, v183, v118
	v_add_f32_e32 v180, v180, v107
	v_add_f32_e32 v181, v181, v111
	v_add_f32_e32 v182, v182, v115
	v_add_f32_e32 v183, v183, v119
	v_add_f32_e32 v180, v180, v181
	v_add_f32_e32 v182, v182, v183
	v_add_f32_e32 v180, v180, v182
	s_nop 1
	v_add_f32_dpp v180, v180, v180 quad_perm:[1,0,3,2] row_mask:0xf bank_mask:0xf
	s_nop 1
	v_add_f32_dpp v180, v180, v180 quad_perm:[2,3,0,1] row_mask:0xf bank_mask:0xf
	s_nop 1
	v_add_f32_dpp v180, v180, v180 row_half_mirror row_mask:0xf bank_mask:0xf
	s_nop 1
	v_add_f32_dpp v180, v180, v180 row_mirror row_mask:0xf bank_mask:0xf
	s_nop 1
	v_add_f32_dpp v180, v180, v180 row_bcast:15 row_mask:0xa bank_mask:0xf
	s_nop 1
	v_add_f32_dpp v180, v180, v180 row_bcast:31 row_mask:0xc bank_mask:0xf
	s_nop 0
	v_readlane_b32 s20, v180, 63
	s_nop 1
	v_mul_f32_e32 v184, s20, v2
	v_sub_f32_e32 v104, v104, v184
	v_sub_f32_e32 v105, v105, v184
	v_sub_f32_e32 v106, v106, v184
	v_sub_f32_e32 v107, v107, v184
	v_sub_f32_e32 v108, v108, v184
	v_sub_f32_e32 v109, v109, v184
	v_sub_f32_e32 v110, v110, v184
	v_sub_f32_e32 v111, v111, v184
	v_sub_f32_e32 v112, v112, v184
	v_sub_f32_e32 v113, v113, v184
	v_sub_f32_e32 v114, v114, v184
	v_sub_f32_e32 v115, v115, v184
	v_sub_f32_e32 v116, v116, v184
	v_sub_f32_e32 v117, v117, v184
	v_sub_f32_e32 v118, v118, v184
	v_sub_f32_e32 v119, v119, v184
	v_mul_f32_e32 v180, v104, v104
	v_mul_f32_e32 v181, v108, v108
	v_mul_f32_e32 v182, v112, v112
	v_mul_f32_e32 v183, v116, v116
	v_fmac_f32_e32 v180, v105, v105
	v_fmac_f32_e32 v181, v109, v109
	v_fmac_f32_e32 v182, v113, v113
	v_fmac_f32_e32 v183, v117, v117
	v_fmac_f32_e32 v180, v106, v106
	v_fmac_f32_e32 v181, v110, v110
	v_fmac_f32_e32 v182, v114, v114
	v_fmac_f32_e32 v183, v118, v118
	v_fmac_f32_e32 v180, v107, v107
	v_fmac_f32_e32 v181, v111, v111
	v_fmac_f32_e32 v182, v115, v115
	v_fmac_f32_e32 v183, v119, v119
	v_add_f32_e32 v180, v180, v181
	v_add_f32_e32 v182, v182, v183
	v_add_f32_e32 v180, v180, v182
	s_nop 1
	v_add_f32_dpp v180, v180, v180 quad_perm:[1,0,3,2] row_mask:0xf bank_mask:0xf
	s_nop 1
	v_add_f32_dpp v180, v180, v180 quad_perm:[2,3,0,1] row_mask:0xf bank_mask:0xf
	s_nop 1
	v_add_f32_dpp v180, v180, v180 row_half_mirror row_mask:0xf bank_mask:0xf
	s_nop 1
	v_add_f32_dpp v180, v180, v180 row_mirror row_mask:0xf bank_mask:0xf
	s_nop 1
	v_add_f32_dpp v180, v180, v180 row_bcast:15 row_mask:0xa bank_mask:0xf
	s_nop 1
	v_add_f32_dpp v180, v180, v180 row_bcast:31 row_mask:0xc bank_mask:0xf
	s_nop 0
	v_readlane_b32 s20, v180, 63
	s_nop 1
	v_mov_b32_e32 v185, s20
	v_fma_f32 v185, v185, v2, v4
	v_rsq_f32_e32 v185, v185
	s_nop 0
	v_mul_f32_e32 v104, v104, v185
	v_mul_f32_e32 v105, v105, v185
	v_mul_f32_e32 v106, v106, v185
	v_mul_f32_e32 v107, v107, v185
	v_mul_f32_e32 v108, v108, v185
	v_mul_f32_e32 v109, v109, v185
	v_mul_f32_e32 v110, v110, v185
	v_mul_f32_e32 v111, v111, v185
	v_mul_f32_e32 v112, v112, v185
	v_mul_f32_e32 v113, v113, v185
	v_mul_f32_e32 v114, v114, v185
	v_mul_f32_e32 v115, v115, v185
	v_mul_f32_e32 v116, v116, v185
	v_mul_f32_e32 v117, v117, v185
	v_mul_f32_e32 v118, v118, v185
	v_mul_f32_e32 v119, v119, v185
	v_fma_f32 v104, v104, v8, v24
	v_fma_f32 v105, v105, v9, v25
	v_fma_f32 v106, v106, v10, v26
	v_fma_f32 v107, v107, v11, v27
	v_fma_f32 v108, v108, v12, v28
	v_fma_f32 v109, v109, v13, v29
	v_fma_f32 v110, v110, v14, v30
	v_fma_f32 v111, v111, v15, v31
	v_fma_f32 v112, v112, v16, v32
	v_fma_f32 v113, v113, v17, v33
	v_fma_f32 v114, v114, v18, v34
	v_fma_f32 v115, v115, v19, v35
	v_fma_f32 v116, v116, v20, v36
	v_fma_f32 v117, v117, v21, v37
	v_fma_f32 v118, v118, v22, v38
	v_fma_f32 v119, v119, v23, v39
	v_add_u32_e32 v171, 0x4000, v1
	global_store_dwordx4 v171, v[104:107], s[4:5]
	global_store_dwordx4 v171, v[108:111], s[4:5] offset:1024
	global_store_dwordx4 v171, v[112:115], s[4:5] offset:2048
	global_store_dwordx4 v171, v[116:119], s[4:5] offset:3072
	s_waitcnt vmcnt(36)
	v_add_f32_e32 v180, v120, v121
	v_add_f32_e32 v181, v124, v125
	v_add_f32_e32 v182, v128, v129
	v_add_f32_e32 v183, v132, v133
	v_add_f32_e32 v180, v180, v122
	v_add_f32_e32 v181, v181, v126
	v_add_f32_e32 v182, v182, v130
	v_add_f32_e32 v183, v183, v134
	v_add_f32_e32 v180, v180, v123
	v_add_f32_e32 v181, v181, v127
	v_add_f32_e32 v182, v182, v131
	v_add_f32_e32 v183, v183, v135
	v_add_f32_e32 v180, v180, v181
	v_add_f32_e32 v182, v182, v183
	v_add_f32_e32 v180, v180, v182
	s_nop 1
	v_add_f32_dpp v180, v180, v180 quad_perm:[1,0,3,2] row_mask:0xf bank_mask:0xf
	s_nop 1
	v_add_f32_dpp v180, v180, v180 quad_perm:[2,3,0,1] row_mask:0xf bank_mask:0xf
	s_nop 1
	v_add_f32_dpp v180, v180, v180 row_half_mirror row_mask:0xf bank_mask:0xf
	s_nop 1
	v_add_f32_dpp v180, v180, v180 row_mirror row_mask:0xf bank_mask:0xf
	s_nop 1
	v_add_f32_dpp v180, v180, v180 row_bcast:15 row_mask:0xa bank_mask:0xf
	s_nop 1
	v_add_f32_dpp v180, v180, v180 row_bcast:31 row_mask:0xc bank_mask:0xf
	s_nop 0
	v_readlane_b32 s20, v180, 63
	s_nop 1
	v_mul_f32_e32 v184, s20, v2
	v_sub_f32_e32 v120, v120, v184
	v_sub_f32_e32 v121, v121, v184
	v_sub_f32_e32 v122, v122, v184
	v_sub_f32_e32 v123, v123, v184
	v_sub_f32_e32 v124, v124, v184
	v_sub_f32_e32 v125, v125, v184
	v_sub_f32_e32 v126, v126, v184
	v_sub_f32_e32 v127, v127, v184
	v_sub_f32_e32 v128, v128, v184
	v_sub_f32_e32 v129, v129, v184
	v_sub_f32_e32 v130, v130, v184
	v_sub_f32_e32 v131, v131, v184
	v_sub_f32_e32 v132, v132, v184
	v_sub_f32_e32 v133, v133, v184
	v_sub_f32_e32 v134, v134, v184
	v_sub_f32_e32 v135, v135, v184
	v_mul_f32_e32 v180, v120, v120
	v_mul_f32_e32 v181, v124, v124
	v_mul_f32_e32 v182, v128, v128
	v_mul_f32_e32 v183, v132, v132
	v_fmac_f32_e32 v180, v121, v121
	v_fmac_f32_e32 v181, v125, v125
	v_fmac_f32_e32 v182, v129, v129
	v_fmac_f32_e32 v183, v133, v133
	v_fmac_f32_e32 v180, v122, v122
	v_fmac_f32_e32 v181, v126, v126
	v_fmac_f32_e32 v182, v130, v130
	v_fmac_f32_e32 v183, v134, v134
	v_fmac_f32_e32 v180, v123, v123
	v_fmac_f32_e32 v181, v127, v127
	v_fmac_f32_e32 v182, v131, v131
	v_fmac_f32_e32 v183, v135, v135
	v_add_f32_e32 v180, v180, v181
	v_add_f32_e32 v182, v182, v183
	v_add_f32_e32 v180, v180, v182
	s_nop 1
	v_add_f32_dpp v180, v180, v180 quad_perm:[1,0,3,2] row_mask:0xf bank_mask:0xf
	s_nop 1
	v_add_f32_dpp v180, v180, v180 quad_perm:[2,3,0,1] row_mask:0xf bank_mask:0xf
	s_nop 1
	v_add_f32_dpp v180, v180, v180 row_half_mirror row_mask:0xf bank_mask:0xf
	s_nop 1
	v_add_f32_dpp v180, v180, v180 row_mirror row_mask:0xf bank_mask:0xf
	s_nop 1
	v_add_f32_dpp v180, v180, v180 row_bcast:15 row_mask:0xa bank_mask:0xf
	s_nop 1
	v_add_f32_dpp v180, v180, v180 row_bcast:31 row_mask:0xc bank_mask:0xf
	s_nop 0
	v_readlane_b32 s20, v180, 63
	s_nop 1
	v_mov_b32_e32 v185, s20
	v_fma_f32 v185, v185, v2, v4
	v_rsq_f32_e32 v185, v185
	s_nop 0
	v_mul_f32_e32 v120, v120, v185
	v_mul_f32_e32 v121, v121, v185
	v_mul_f32_e32 v122, v122, v185
	v_mul_f32_e32 v123, v123, v185
	v_mul_f32_e32 v124, v124, v185
	v_mul_f32_e32 v125, v125, v185
	v_mul_f32_e32 v126, v126, v185
	v_mul_f32_e32 v127, v127, v185
	v_mul_f32_e32 v128, v128, v185
	v_mul_f32_e32 v129, v129, v185
	v_mul_f32_e32 v130, v130, v185
	v_mul_f32_e32 v131, v131, v185
	v_mul_f32_e32 v132, v132, v185
	v_mul_f32_e32 v133, v133, v185
	v_mul_f32_e32 v134, v134, v185
	v_mul_f32_e32 v135, v135, v185
	v_fma_f32 v120, v120, v8, v24
	v_fma_f32 v121, v121, v9, v25
	v_fma_f32 v122, v122, v10, v26
	v_fma_f32 v123, v123, v11, v27
	v_fma_f32 v124, v124, v12, v28
	v_fma_f32 v125, v125, v13, v29
	v_fma_f32 v126, v126, v14, v30
	v_fma_f32 v127, v127, v15, v31
	v_fma_f32 v128, v128, v16, v32
	v_fma_f32 v129, v129, v17, v33
	v_fma_f32 v130, v130, v18, v34
	v_fma_f32 v131, v131, v19, v35
	v_fma_f32 v132, v132, v20, v36
	v_fma_f32 v133, v133, v21, v37
	v_fma_f32 v134, v134, v22, v38
	v_fma_f32 v135, v135, v23, v39
	v_add_u32_e32 v171, 0x5000, v1
	global_store_dwordx4 v171, v[120:123], s[4:5]
	global_store_dwordx4 v171, v[124:127], s[4:5] offset:1024
	global_store_dwordx4 v171, v[128:131], s[4:5] offset:2048
	global_store_dwordx4 v171, v[132:135], s[4:5] offset:3072
	s_waitcnt vmcnt(36)
	v_add_f32_e32 v180, v136, v137
	v_add_f32_e32 v181, v140, v141
	v_add_f32_e32 v182, v144, v145
	v_add_f32_e32 v183, v148, v149
	v_add_f32_e32 v180, v180, v138
	v_add_f32_e32 v181, v181, v142
	v_add_f32_e32 v182, v182, v146
	v_add_f32_e32 v183, v183, v150
	v_add_f32_e32 v180, v180, v139
	v_add_f32_e32 v181, v181, v143
	v_add_f32_e32 v182, v182, v147
	v_add_f32_e32 v183, v183, v151
	v_add_f32_e32 v180, v180, v181
	v_add_f32_e32 v182, v182, v183
	v_add_f32_e32 v180, v180, v182
	s_nop 1
	v_add_f32_dpp v180, v180, v180 quad_perm:[1,0,3,2] row_mask:0xf bank_mask:0xf
	s_nop 1
	v_add_f32_dpp v180, v180, v180 quad_perm:[2,3,0,1] row_mask:0xf bank_mask:0xf
	s_nop 1
	v_add_f32_dpp v180, v180, v180 row_half_mirror row_mask:0xf bank_mask:0xf
	s_nop 1
	v_add_f32_dpp v180, v180, v180 row_mirror row_mask:0xf bank_mask:0xf
	s_nop 1
	v_add_f32_dpp v180, v180, v180 row_bcast:15 row_mask:0xa bank_mask:0xf
	s_nop 1
	v_add_f32_dpp v180, v180, v180 row_bcast:31 row_mask:0xc bank_mask:0xf
	s_nop 0
	v_readlane_b32 s20, v180, 63
	s_nop 1
	v_mul_f32_e32 v184, s20, v2
	v_sub_f32_e32 v136, v136, v184
	v_sub_f32_e32 v137, v137, v184
	v_sub_f32_e32 v138, v138, v184
	v_sub_f32_e32 v139, v139, v184
	v_sub_f32_e32 v140, v140, v184
	v_sub_f32_e32 v141, v141, v184
	v_sub_f32_e32 v142, v142, v184
	v_sub_f32_e32 v143, v143, v184
	v_sub_f32_e32 v144, v144, v184
	v_sub_f32_e32 v145, v145, v184
	v_sub_f32_e32 v146, v146, v184
	v_sub_f32_e32 v147, v147, v184
	v_sub_f32_e32 v148, v148, v184
	v_sub_f32_e32 v149, v149, v184
	v_sub_f32_e32 v150, v150, v184
	v_sub_f32_e32 v151, v151, v184
	v_mul_f32_e32 v180, v136, v136
	v_mul_f32_e32 v181, v140, v140
	v_mul_f32_e32 v182, v144, v144
	v_mul_f32_e32 v183, v148, v148
	v_fmac_f32_e32 v180, v137, v137
	v_fmac_f32_e32 v181, v141, v141
	v_fmac_f32_e32 v182, v145, v145
	v_fmac_f32_e32 v183, v149, v149
	v_fmac_f32_e32 v180, v138, v138
	v_fmac_f32_e32 v181, v142, v142
	v_fmac_f32_e32 v182, v146, v146
	v_fmac_f32_e32 v183, v150, v150
	v_fmac_f32_e32 v180, v139, v139
	v_fmac_f32_e32 v181, v143, v143
	v_fmac_f32_e32 v182, v147, v147
	v_fmac_f32_e32 v183, v151, v151
	v_add_f32_e32 v180, v180, v181
	v_add_f32_e32 v182, v182, v183
	v_add_f32_e32 v180, v180, v182
	s_nop 1
	v_add_f32_dpp v180, v180, v180 quad_perm:[1,0,3,2] row_mask:0xf bank_mask:0xf
	s_nop 1
	v_add_f32_dpp v180, v180, v180 quad_perm:[2,3,0,1] row_mask:0xf bank_mask:0xf
	s_nop 1
	v_add_f32_dpp v180, v180, v180 row_half_mirror row_mask:0xf bank_mask:0xf
	s_nop 1
	v_add_f32_dpp v180, v180, v180 row_mirror row_mask:0xf bank_mask:0xf
	s_nop 1
	v_add_f32_dpp v180, v180, v180 row_bcast:15 row_mask:0xa bank_mask:0xf
	s_nop 1
	v_add_f32_dpp v180, v180, v180 row_bcast:31 row_mask:0xc bank_mask:0xf
	s_nop 0
	v_readlane_b32 s20, v180, 63
	s_nop 1
	v_mov_b32_e32 v185, s20
	v_fma_f32 v185, v185, v2, v4
	v_rsq_f32_e32 v185, v185
	s_nop 0
	v_mul_f32_e32 v136, v136, v185
	v_mul_f32_e32 v137, v137, v185
	v_mul_f32_e32 v138, v138, v185
	v_mul_f32_e32 v139, v139, v185
	v_mul_f32_e32 v140, v140, v185
	v_mul_f32_e32 v141, v141, v185
	v_mul_f32_e32 v142, v142, v185
	v_mul_f32_e32 v143, v143, v185
	v_mul_f32_e32 v144, v144, v185
	v_mul_f32_e32 v145, v145, v185
	v_mul_f32_e32 v146, v146, v185
	v_mul_f32_e32 v147, v147, v185
	v_mul_f32_e32 v148, v148, v185
	v_mul_f32_e32 v149, v149, v185
	v_mul_f32_e32 v150, v150, v185
	v_mul_f32_e32 v151, v151, v185
	v_fma_f32 v136, v136, v8, v24
	v_fma_f32 v137, v137, v9, v25
	v_fma_f32 v138, v138, v10, v26
	v_fma_f32 v139, v139, v11, v27
	v_fma_f32 v140, v140, v12, v28
	v_fma_f32 v141, v141, v13, v29
	v_fma_f32 v142, v142, v14, v30
	v_fma_f32 v143, v143, v15, v31
	v_fma_f32 v144, v144, v16, v32
	v_fma_f32 v145, v145, v17, v33
	v_fma_f32 v146, v146, v18, v34
	v_fma_f32 v147, v147, v19, v35
	v_fma_f32 v148, v148, v20, v36
	v_fma_f32 v149, v149, v21, v37
	v_fma_f32 v150, v150, v22, v38
	v_fma_f32 v151, v151, v23, v39
	v_add_u32_e32 v171, 0x6000, v1
	global_store_dwordx4 v171, v[136:139], s[4:5]
	global_store_dwordx4 v171, v[140:143], s[4:5] offset:1024
	global_store_dwordx4 v171, v[144:147], s[4:5] offset:2048
	global_store_dwordx4 v171, v[148:151], s[4:5] offset:3072
	s_waitcnt vmcnt(36)
	v_add_f32_e32 v180, v152, v153
	v_add_f32_e32 v181, v156, v157
	v_add_f32_e32 v182, v160, v161
	v_add_f32_e32 v183, v164, v165
	v_add_f32_e32 v180, v180, v154
	v_add_f32_e32 v181, v181, v158
	v_add_f32_e32 v182, v182, v162
	v_add_f32_e32 v183, v183, v166
	v_add_f32_e32 v180, v180, v155
	v_add_f32_e32 v181, v181, v159
	v_add_f32_e32 v182, v182, v163
	v_add_f32_e32 v183, v183, v167
	v_add_f32_e32 v180, v180, v181
	v_add_f32_e32 v182, v182, v183
	v_add_f32_e32 v180, v180, v182
	s_nop 1
	v_add_f32_dpp v180, v180, v180 quad_perm:[1,0,3,2] row_mask:0xf bank_mask:0xf
	s_nop 1
	v_add_f32_dpp v180, v180, v180 quad_perm:[2,3,0,1] row_mask:0xf bank_mask:0xf
	s_nop 1
	v_add_f32_dpp v180, v180, v180 row_half_mirror row_mask:0xf bank_mask:0xf
	s_nop 1
	v_add_f32_dpp v180, v180, v180 row_mirror row_mask:0xf bank_mask:0xf
	s_nop 1
	v_add_f32_dpp v180, v180, v180 row_bcast:15 row_mask:0xa bank_mask:0xf
	s_nop 1
	v_add_f32_dpp v180, v180, v180 row_bcast:31 row_mask:0xc bank_mask:0xf
	s_nop 0
	v_readlane_b32 s20, v180, 63
	s_nop 1
	v_mul_f32_e32 v184, s20, v2
	v_sub_f32_e32 v152, v152, v184
	v_sub_f32_e32 v153, v153, v184
	v_sub_f32_e32 v154, v154, v184
	v_sub_f32_e32 v155, v155, v184
	v_sub_f32_e32 v156, v156, v184
	v_sub_f32_e32 v157, v157, v184
	v_sub_f32_e32 v158, v158, v184
	v_sub_f32_e32 v159, v159, v184
	v_sub_f32_e32 v160, v160, v184
	v_sub_f32_e32 v161, v161, v184
	v_sub_f32_e32 v162, v162, v184
	v_sub_f32_e32 v163, v163, v184
	v_sub_f32_e32 v164, v164, v184
	v_sub_f32_e32 v165, v165, v184
	v_sub_f32_e32 v166, v166, v184
	v_sub_f32_e32 v167, v167, v184
	v_mul_f32_e32 v180, v152, v152
	v_mul_f32_e32 v181, v156, v156
	v_mul_f32_e32 v182, v160, v160
	v_mul_f32_e32 v183, v164, v164
	v_fmac_f32_e32 v180, v153, v153
	v_fmac_f32_e32 v181, v157, v157
	v_fmac_f32_e32 v182, v161, v161
	v_fmac_f32_e32 v183, v165, v165
	v_fmac_f32_e32 v180, v154, v154
	v_fmac_f32_e32 v181, v158, v158
	v_fmac_f32_e32 v182, v162, v162
	v_fmac_f32_e32 v183, v166, v166
	v_fmac_f32_e32 v180, v155, v155
	v_fmac_f32_e32 v181, v159, v159
	v_fmac_f32_e32 v182, v163, v163
	v_fmac_f32_e32 v183, v167, v167
	v_add_f32_e32 v180, v180, v181
	v_add_f32_e32 v182, v182, v183
	v_add_f32_e32 v180, v180, v182
	s_nop 1
	v_add_f32_dpp v180, v180, v180 quad_perm:[1,0,3,2] row_mask:0xf bank_mask:0xf
	s_nop 1
	v_add_f32_dpp v180, v180, v180 quad_perm:[2,3,0,1] row_mask:0xf bank_mask:0xf
	s_nop 1
	v_add_f32_dpp v180, v180, v180 row_half_mirror row_mask:0xf bank_mask:0xf
	s_nop 1
	v_add_f32_dpp v180, v180, v180 row_mirror row_mask:0xf bank_mask:0xf
	s_nop 1
	v_add_f32_dpp v180, v180, v180 row_bcast:15 row_mask:0xa bank_mask:0xf
	s_nop 1
	v_add_f32_dpp v180, v180, v180 row_bcast:31 row_mask:0xc bank_mask:0xf
	s_nop 0
	v_readlane_b32 s20, v180, 63
	s_nop 1
	v_mov_b32_e32 v185, s20
	v_fma_f32 v185, v185, v2, v4
	v_rsq_f32_e32 v185, v185
	s_nop 0
	v_mul_f32_e32 v152, v152, v185
	v_mul_f32_e32 v153, v153, v185
	v_mul_f32_e32 v154, v154, v185
	v_mul_f32_e32 v155, v155, v185
	v_mul_f32_e32 v156, v156, v185
	v_mul_f32_e32 v157, v157, v185
	v_mul_f32_e32 v158, v158, v185
	v_mul_f32_e32 v159, v159, v185
	v_mul_f32_e32 v160, v160, v185
	v_mul_f32_e32 v161, v161, v185
	v_mul_f32_e32 v162, v162, v185
	v_mul_f32_e32 v163, v163, v185
	v_mul_f32_e32 v164, v164, v185
	v_mul_f32_e32 v165, v165, v185
	v_mul_f32_e32 v166, v166, v185
	v_mul_f32_e32 v167, v167, v185
	v_fma_f32 v152, v152, v8, v24
	v_fma_f32 v153, v153, v9, v25
	v_fma_f32 v154, v154, v10, v26
	v_fma_f32 v155, v155, v11, v27
	v_fma_f32 v156, v156, v12, v28
	v_fma_f32 v157, v157, v13, v29
	v_fma_f32 v158, v158, v14, v30
	v_fma_f32 v159, v159, v15, v31
	v_fma_f32 v160, v160, v16, v32
	v_fma_f32 v161, v161, v17, v33
	v_fma_f32 v162, v162, v18, v34
	v_fma_f32 v163, v163, v19, v35
	v_fma_f32 v164, v164, v20, v36
	v_fma_f32 v165, v165, v21, v37
	v_fma_f32 v166, v166, v22, v38
	v_fma_f32 v167, v167, v23, v39
	v_add_u32_e32 v171, 0x7000, v1
	global_store_dwordx4 v171, v[152:155], s[4:5]
	global_store_dwordx4 v171, v[156:159], s[4:5] offset:1024
	global_store_dwordx4 v171, v[160:163], s[4:5] offset:2048
	global_store_dwordx4 v171, v[164:167], s[4:5] offset:3072
	s_waitcnt vmcnt(32)
	v_add_f32_e32 v180, v40, v41
	v_add_f32_e32 v181, v44, v45
	v_add_f32_e32 v182, v48, v49
	v_add_f32_e32 v183, v52, v53
	v_add_f32_e32 v180, v180, v42
	v_add_f32_e32 v181, v181, v46
	v_add_f32_e32 v182, v182, v50
	v_add_f32_e32 v183, v183, v54
	v_add_f32_e32 v180, v180, v43
	v_add_f32_e32 v181, v181, v47
	v_add_f32_e32 v182, v182, v51
	v_add_f32_e32 v183, v183, v55
	v_add_f32_e32 v180, v180, v181
	v_add_f32_e32 v182, v182, v183
	v_add_f32_e32 v180, v180, v182
	s_nop 1
	v_add_f32_dpp v180, v180, v180 quad_perm:[1,0,3,2] row_mask:0xf bank_mask:0xf
	s_nop 1
	v_add_f32_dpp v180, v180, v180 quad_perm:[2,3,0,1] row_mask:0xf bank_mask:0xf
	s_nop 1
	v_add_f32_dpp v180, v180, v180 row_half_mirror row_mask:0xf bank_mask:0xf
	s_nop 1
	v_add_f32_dpp v180, v180, v180 row_mirror row_mask:0xf bank_mask:0xf
	s_nop 1
	v_add_f32_dpp v180, v180, v180 row_bcast:15 row_mask:0xa bank_mask:0xf
	s_nop 1
	v_add_f32_dpp v180, v180, v180 row_bcast:31 row_mask:0xc bank_mask:0xf
	s_nop 0
	v_readlane_b32 s20, v180, 63
	s_nop 1
	v_mul_f32_e32 v184, s20, v2
	v_sub_f32_e32 v40, v40, v184
	v_sub_f32_e32 v41, v41, v184
	v_sub_f32_e32 v42, v42, v184
	v_sub_f32_e32 v43, v43, v184
	v_sub_f32_e32 v44, v44, v184
	v_sub_f32_e32 v45, v45, v184
	v_sub_f32_e32 v46, v46, v184
	v_sub_f32_e32 v47, v47, v184
	v_sub_f32_e32 v48, v48, v184
	v_sub_f32_e32 v49, v49, v184
	v_sub_f32_e32 v50, v50, v184
	v_sub_f32_e32 v51, v51, v184
	v_sub_f32_e32 v52, v52, v184
	v_sub_f32_e32 v53, v53, v184
	v_sub_f32_e32 v54, v54, v184
	v_sub_f32_e32 v55, v55, v184
	v_mul_f32_e32 v180, v40, v40
	v_mul_f32_e32 v181, v44, v44
	v_mul_f32_e32 v182, v48, v48
	v_mul_f32_e32 v183, v52, v52
	v_fmac_f32_e32 v180, v41, v41
	v_fmac_f32_e32 v181, v45, v45
	v_fmac_f32_e32 v182, v49, v49
	v_fmac_f32_e32 v183, v53, v53
	v_fmac_f32_e32 v180, v42, v42
	v_fmac_f32_e32 v181, v46, v46
	v_fmac_f32_e32 v182, v50, v50
	v_fmac_f32_e32 v183, v54, v54
	v_fmac_f32_e32 v180, v43, v43
	v_fmac_f32_e32 v181, v47, v47
	v_fmac_f32_e32 v182, v51, v51
	v_fmac_f32_e32 v183, v55, v55
	v_add_f32_e32 v180, v180, v181
	v_add_f32_e32 v182, v182, v183
	v_add_f32_e32 v180, v180, v182
	s_nop 1
	v_add_f32_dpp v180, v180, v180 quad_perm:[1,0,3,2] row_mask:0xf bank_mask:0xf
	s_nop 1
	v_add_f32_dpp v180, v180, v180 quad_perm:[2,3,0,1] row_mask:0xf bank_mask:0xf
	s_nop 1
	v_add_f32_dpp v180, v180, v180 row_half_mirror row_mask:0xf bank_mask:0xf
	s_nop 1
	v_add_f32_dpp v180, v180, v180 row_mirror row_mask:0xf bank_mask:0xf
	s_nop 1
	v_add_f32_dpp v180, v180, v180 row_bcast:15 row_mask:0xa bank_mask:0xf
	s_nop 1
	v_add_f32_dpp v180, v180, v180 row_bcast:31 row_mask:0xc bank_mask:0xf
	s_nop 0
	v_readlane_b32 s20, v180, 63
	s_nop 1
	v_mov_b32_e32 v185, s20
	v_fma_f32 v185, v185, v2, v4
	v_rsq_f32_e32 v185, v185
	s_nop 0
	v_mul_f32_e32 v40, v40, v185
	v_mul_f32_e32 v41, v41, v185
	v_mul_f32_e32 v42, v42, v185
	v_mul_f32_e32 v43, v43, v185
	v_mul_f32_e32 v44, v44, v185
	v_mul_f32_e32 v45, v45, v185
	v_mul_f32_e32 v46, v46, v185
	v_mul_f32_e32 v47, v47, v185
	v_mul_f32_e32 v48, v48, v185
	v_mul_f32_e32 v49, v49, v185
	v_mul_f32_e32 v50, v50, v185
	v_mul_f32_e32 v51, v51, v185
	v_mul_f32_e32 v52, v52, v185
	v_mul_f32_e32 v53, v53, v185
	v_mul_f32_e32 v54, v54, v185
	v_mul_f32_e32 v55, v55, v185
	v_fma_f32 v40, v40, v8, v24
	v_fma_f32 v41, v41, v9, v25
	v_fma_f32 v42, v42, v10, v26
	v_fma_f32 v43, v43, v11, v27
	v_fma_f32 v44, v44, v12, v28
	v_fma_f32 v45, v45, v13, v29
	v_fma_f32 v46, v46, v14, v30
	v_fma_f32 v47, v47, v15, v31
	v_fma_f32 v48, v48, v16, v32
	v_fma_f32 v49, v49, v17, v33
	v_fma_f32 v50, v50, v18, v34
	v_fma_f32 v51, v51, v19, v35
	v_fma_f32 v52, v52, v20, v36
	v_fma_f32 v53, v53, v21, v37
	v_fma_f32 v54, v54, v22, v38
	v_fma_f32 v55, v55, v23, v39
	v_add_u32_e32 v171, 0x8000, v1
	global_store_dwordx4 v171, v[40:43], s[4:5]
	global_store_dwordx4 v171, v[44:47], s[4:5] offset:1024
	global_store_dwordx4 v171, v[48:51], s[4:5] offset:2048
	global_store_dwordx4 v171, v[52:55], s[4:5] offset:3072
	s_waitcnt vmcnt(28)
	v_add_f32_e32 v180, v56, v57
	v_add_f32_e32 v181, v60, v61
	v_add_f32_e32 v182, v64, v65
	v_add_f32_e32 v183, v68, v69
	v_add_f32_e32 v180, v180, v58
	v_add_f32_e32 v181, v181, v62
	v_add_f32_e32 v182, v182, v66
	v_add_f32_e32 v183, v183, v70
	v_add_f32_e32 v180, v180, v59
	v_add_f32_e32 v181, v181, v63
	v_add_f32_e32 v182, v182, v67
	v_add_f32_e32 v183, v183, v71
	v_add_f32_e32 v180, v180, v181
	v_add_f32_e32 v182, v182, v183
	v_add_f32_e32 v180, v180, v182
	s_nop 1
	v_add_f32_dpp v180, v180, v180 quad_perm:[1,0,3,2] row_mask:0xf bank_mask:0xf
	s_nop 1
	v_add_f32_dpp v180, v180, v180 quad_perm:[2,3,0,1] row_mask:0xf bank_mask:0xf
	s_nop 1
	v_add_f32_dpp v180, v180, v180 row_half_mirror row_mask:0xf bank_mask:0xf
	s_nop 1
	v_add_f32_dpp v180, v180, v180 row_mirror row_mask:0xf bank_mask:0xf
	s_nop 1
	v_add_f32_dpp v180, v180, v180 row_bcast:15 row_mask:0xa bank_mask:0xf
	s_nop 1
	v_add_f32_dpp v180, v180, v180 row_bcast:31 row_mask:0xc bank_mask:0xf
	s_nop 0
	v_readlane_b32 s20, v180, 63
	s_nop 1
	v_mul_f32_e32 v184, s20, v2
	v_sub_f32_e32 v56, v56, v184
	v_sub_f32_e32 v57, v57, v184
	v_sub_f32_e32 v58, v58, v184
	v_sub_f32_e32 v59, v59, v184
	v_sub_f32_e32 v60, v60, v184
	v_sub_f32_e32 v61, v61, v184
	v_sub_f32_e32 v62, v62, v184
	v_sub_f32_e32 v63, v63, v184
	v_sub_f32_e32 v64, v64, v184
	v_sub_f32_e32 v65, v65, v184
	v_sub_f32_e32 v66, v66, v184
	v_sub_f32_e32 v67, v67, v184
	v_sub_f32_e32 v68, v68, v184
	v_sub_f32_e32 v69, v69, v184
	v_sub_f32_e32 v70, v70, v184
	v_sub_f32_e32 v71, v71, v184
	v_mul_f32_e32 v180, v56, v56
	v_mul_f32_e32 v181, v60, v60
	v_mul_f32_e32 v182, v64, v64
	v_mul_f32_e32 v183, v68, v68
	v_fmac_f32_e32 v180, v57, v57
	v_fmac_f32_e32 v181, v61, v61
	v_fmac_f32_e32 v182, v65, v65
	v_fmac_f32_e32 v183, v69, v69
	v_fmac_f32_e32 v180, v58, v58
	v_fmac_f32_e32 v181, v62, v62
	v_fmac_f32_e32 v182, v66, v66
	v_fmac_f32_e32 v183, v70, v70
	v_fmac_f32_e32 v180, v59, v59
	v_fmac_f32_e32 v181, v63, v63
	v_fmac_f32_e32 v182, v67, v67
	v_fmac_f32_e32 v183, v71, v71
	v_add_f32_e32 v180, v180, v181
	v_add_f32_e32 v182, v182, v183
	v_add_f32_e32 v180, v180, v182
	s_nop 1
	v_add_f32_dpp v180, v180, v180 quad_perm:[1,0,3,2] row_mask:0xf bank_mask:0xf
	s_nop 1
	v_add_f32_dpp v180, v180, v180 quad_perm:[2,3,0,1] row_mask:0xf bank_mask:0xf
	s_nop 1
	v_add_f32_dpp v180, v180, v180 row_half_mirror row_mask:0xf bank_mask:0xf
	s_nop 1
	v_add_f32_dpp v180, v180, v180 row_mirror row_mask:0xf bank_mask:0xf
	s_nop 1
	v_add_f32_dpp v180, v180, v180 row_bcast:15 row_mask:0xa bank_mask:0xf
	s_nop 1
	v_add_f32_dpp v180, v180, v180 row_bcast:31 row_mask:0xc bank_mask:0xf
	s_nop 0
	v_readlane_b32 s20, v180, 63
	s_nop 1
	v_mov_b32_e32 v185, s20
	v_fma_f32 v185, v185, v2, v4
	v_rsq_f32_e32 v185, v185
	s_nop 0
	v_mul_f32_e32 v56, v56, v185
	v_mul_f32_e32 v57, v57, v185
	v_mul_f32_e32 v58, v58, v185
	v_mul_f32_e32 v59, v59, v185
	v_mul_f32_e32 v60, v60, v185
	v_mul_f32_e32 v61, v61, v185
	v_mul_f32_e32 v62, v62, v185
	v_mul_f32_e32 v63, v63, v185
	v_mul_f32_e32 v64, v64, v185
	v_mul_f32_e32 v65, v65, v185
	v_mul_f32_e32 v66, v66, v185
	v_mul_f32_e32 v67, v67, v185
	v_mul_f32_e32 v68, v68, v185
	v_mul_f32_e32 v69, v69, v185
	v_mul_f32_e32 v70, v70, v185
	v_mul_f32_e32 v71, v71, v185
	v_fma_f32 v56, v56, v8, v24
	v_fma_f32 v57, v57, v9, v25
	v_fma_f32 v58, v58, v10, v26
	v_fma_f32 v59, v59, v11, v27
	v_fma_f32 v60, v60, v12, v28
	v_fma_f32 v61, v61, v13, v29
	v_fma_f32 v62, v62, v14, v30
	v_fma_f32 v63, v63, v15, v31
	v_fma_f32 v64, v64, v16, v32
	v_fma_f32 v65, v65, v17, v33
	v_fma_f32 v66, v66, v18, v34
	v_fma_f32 v67, v67, v19, v35
	v_fma_f32 v68, v68, v20, v36
	v_fma_f32 v69, v69, v21, v37
	v_fma_f32 v70, v70, v22, v38
	v_fma_f32 v71, v71, v23, v39
	v_add_u32_e32 v171, 0x9000, v1
	global_store_dwordx4 v171, v[56:59], s[4:5]
	global_store_dwordx4 v171, v[60:63], s[4:5] offset:1024
	global_store_dwordx4 v171, v[64:67], s[4:5] offset:2048
	global_store_dwordx4 v171, v[68:71], s[4:5] offset:3072
	s_branch .Ltr_29
.Llo_small:
	s_lshr_b32 s1, s86, 3
	s_mul_i32 s1, s1, 16
	s_mul_i32 s0, s0, 2
	s_add_i32 s0, s0, s1
	s_and_b32 s1, s86, 7
	s_lshl_b32 s1, s1, 11
	s_add_i32 s0, s0, s1
	s_lshl_b32 s0, s0, 12
	s_add_u32 s4, s4, s0
	s_addc_u32 s5, s5, 0
	global_load_dwordx4 v[40:43], v1, s[4:5]
	global_load_dwordx4 v[44:47], v1, s[4:5] offset:1024
	global_load_dwordx4 v[48:51], v1, s[4:5] offset:2048
	global_load_dwordx4 v[52:55], v1, s[4:5] offset:3072
	global_load_dwordx4 v[8:11], v1, s[40:41]
	global_load_dwordx4 v[12:15], v1, s[40:41] offset:1024
	global_load_dwordx4 v[16:19], v1, s[40:41] offset:2048
	global_load_dwordx4 v[20:23], v1, s[40:41] offset:3072
	global_load_dwordx4 v[24:27], v1, s[42:43]
	global_load_dwordx4 v[28:31], v1, s[42:43] offset:1024
	global_load_dwordx4 v[32:35], v1, s[42:43] offset:2048
	global_load_dwordx4 v[36:39], v1, s[42:43] offset:3072
	v_add_u32_e32 v170, 0x1000, v1
	global_load_dwordx4 v[56:59], v170, s[4:5]
	global_load_dwordx4 v[60:63], v170, s[4:5] offset:1024
	global_load_dwordx4 v[64:67], v170, s[4:5] offset:2048
	global_load_dwordx4 v[68:71], v170, s[4:5] offset:3072
	s_waitcnt vmcnt(12)
	v_add_f32_e32 v180, v40, v41
	v_add_f32_e32 v181, v44, v45
	v_add_f32_e32 v182, v48, v49
	v_add_f32_e32 v183, v52, v53
	v_add_f32_e32 v180, v180, v42
	v_add_f32_e32 v181, v181, v46
	v_add_f32_e32 v182, v182, v50
	v_add_f32_e32 v183, v183, v54
	v_add_f32_e32 v180, v180, v43
	v_add_f32_e32 v181, v181, v47
	v_add_f32_e32 v182, v182, v51
	v_add_f32_e32 v183, v183, v55
	v_add_f32_e32 v180, v180, v181
	v_add_f32_e32 v182, v182, v183
	v_add_f32_e32 v180, v180, v182
	s_nop 1
	v_add_f32_dpp v180, v180, v180 quad_perm:[1,0,3,2] row_mask:0xf bank_mask:0xf
	s_nop 1
	v_add_f32_dpp v180, v180, v180 quad_perm:[2,3,0,1] row_mask:0xf bank_mask:0xf
	s_nop 1
	v_add_f32_dpp v180, v180, v180 row_half_mirror row_mask:0xf bank_mask:0xf
	s_nop 1
	v_add_f32_dpp v180, v180, v180 row_mirror row_mask:0xf bank_mask:0xf
	s_nop 1
	v_add_f32_dpp v180, v180, v180 row_bcast:15 row_mask:0xa bank_mask:0xf
	s_nop 1
	v_add_f32_dpp v180, v180, v180 row_bcast:31 row_mask:0xc bank_mask:0xf
	s_nop 0
	v_readlane_b32 s20, v180, 63
	s_nop 1
	v_mul_f32_e32 v184, s20, v2
	v_sub_f32_e32 v40, v40, v184
	v_sub_f32_e32 v41, v41, v184
	v_sub_f32_e32 v42, v42, v184
	v_sub_f32_e32 v43, v43, v184
	v_sub_f32_e32 v44, v44, v184
	v_sub_f32_e32 v45, v45, v184
	v_sub_f32_e32 v46, v46, v184
	v_sub_f32_e32 v47, v47, v184
	v_sub_f32_e32 v48, v48, v184
	v_sub_f32_e32 v49, v49, v184
	v_sub_f32_e32 v50, v50, v184
	v_sub_f32_e32 v51, v51, v184
	v_sub_f32_e32 v52, v52, v184
	v_sub_f32_e32 v53, v53, v184
	v_sub_f32_e32 v54, v54, v184
	v_sub_f32_e32 v55, v55, v184
	v_mul_f32_e32 v180, v40, v40
	v_mul_f32_e32 v181, v44, v44
	v_mul_f32_e32 v182, v48, v48
	v_mul_f32_e32 v183, v52, v52
	v_fmac_f32_e32 v180, v41, v41
	v_fmac_f32_e32 v181, v45, v45
	v_fmac_f32_e32 v182, v49, v49
	v_fmac_f32_e32 v183, v53, v53
	v_fmac_f32_e32 v180, v42, v42
	v_fmac_f32_e32 v181, v46, v46
	v_fmac_f32_e32 v182, v50, v50
	v_fmac_f32_e32 v183, v54, v54
	v_fmac_f32_e32 v180, v43, v43
	v_fmac_f32_e32 v181, v47, v47
	v_fmac_f32_e32 v182, v51, v51
	v_fmac_f32_e32 v183, v55, v55
	v_add_f32_e32 v180, v180, v181
	v_add_f32_e32 v182, v182, v183
	v_add_f32_e32 v180, v180, v182
	s_nop 1
	v_add_f32_dpp v180, v180, v180 quad_perm:[1,0,3,2] row_mask:0xf bank_mask:0xf
	s_nop 1
	v_add_f32_dpp v180, v180, v180 quad_perm:[2,3,0,1] row_mask:0xf bank_mask:0xf
	s_nop 1
	v_add_f32_dpp v180, v180, v180 row_half_mirror row_mask:0xf bank_mask:0xf
	s_nop 1
	v_add_f32_dpp v180, v180, v180 row_mirror row_mask:0xf bank_mask:0xf
	s_nop 1
	v_add_f32_dpp v180, v180, v180 row_bcast:15 row_mask:0xa bank_mask:0xf
	s_nop 1
	v_add_f32_dpp v180, v180, v180 row_bcast:31 row_mask:0xc bank_mask:0xf
	s_nop 0
	v_readlane_b32 s20, v180, 63
	s_nop 1
	v_mov_b32_e32 v185, s20
	v_fma_f32 v185, v185, v2, v4
	v_rsq_f32_e32 v185, v185
	s_nop 0
	v_mul_f32_e32 v40, v40, v185
	v_mul_f32_e32 v41, v41, v185
	v_mul_f32_e32 v42, v42, v185
	v_mul_f32_e32 v43, v43, v185
	v_mul_f32_e32 v44, v44, v185
	v_mul_f32_e32 v45, v45, v185
	v_mul_f32_e32 v46, v46, v185
	v_mul_f32_e32 v47, v47, v185
	v_mul_f32_e32 v48, v48, v185
	v_mul_f32_e32 v49, v49, v185
	v_mul_f32_e32 v50, v50, v185
	v_mul_f32_e32 v51, v51, v185
	v_mul_f32_e32 v52, v52, v185
	v_mul_f32_e32 v53, v53, v185
	v_mul_f32_e32 v54, v54, v185
	v_mul_f32_e32 v55, v55, v185
	s_waitcnt vmcnt(4)
	v_fma_f32 v40, v40, v8, v24
	v_fma_f32 v41, v41, v9, v25
	v_fma_f32 v42, v42, v10, v26
	v_fma_f32 v43, v43, v11, v27
	v_fma_f32 v44, v44, v12, v28
	v_fma_f32 v45, v45, v13, v29
	v_fma_f32 v46, v46, v14, v30
	v_fma_f32 v47, v47, v15, v31
	v_fma_f32 v48, v48, v16, v32
	v_fma_f32 v49, v49, v17, v33
	v_fma_f32 v50, v50, v18, v34
	v_fma_f32 v51, v51, v19, v35
	v_fma_f32 v52, v52, v20, v36
	v_fma_f32 v53, v53, v21, v37
	v_fma_f32 v54, v54, v22, v38
	v_fma_f32 v55, v55, v23, v39
	global_store_dwordx4 v1, v[40:43], s[4:5]
	global_store_dwordx4 v1, v[44:47], s[4:5] offset:1024
	global_store_dwordx4 v1, v[48:51], s[4:5] offset:2048
	global_store_dwordx4 v1, v[52:55], s[4:5] offset:3072
	s_waitcnt vmcnt(4)
	v_add_f32_e32 v180, v56, v57
	v_add_f32_e32 v181, v60, v61
	v_add_f32_e32 v182, v64, v65
	v_add_f32_e32 v183, v68, v69
	v_add_f32_e32 v180, v180, v58
	v_add_f32_e32 v181, v181, v62
	v_add_f32_e32 v182, v182, v66
	v_add_f32_e32 v183, v183, v70
	v_add_f32_e32 v180, v180, v59
	v_add_f32_e32 v181, v181, v63
	v_add_f32_e32 v182, v182, v67
	v_add_f32_e32 v183, v183, v71
	v_add_f32_e32 v180, v180, v181
	v_add_f32_e32 v182, v182, v183
	v_add_f32_e32 v180, v180, v182
	s_nop 1
	v_add_f32_dpp v180, v180, v180 quad_perm:[1,0,3,2] row_mask:0xf bank_mask:0xf
	s_nop 1
	v_add_f32_dpp v180, v180, v180 quad_perm:[2,3,0,1] row_mask:0xf bank_mask:0xf
	s_nop 1
	v_add_f32_dpp v180, v180, v180 row_half_mirror row_mask:0xf bank_mask:0xf
	s_nop 1
	v_add_f32_dpp v180, v180, v180 row_mirror row_mask:0xf bank_mask:0xf
	s_nop 1
	v_add_f32_dpp v180, v180, v180 row_bcast:15 row_mask:0xa bank_mask:0xf
	s_nop 1
	v_add_f32_dpp v180, v180, v180 row_bcast:31 row_mask:0xc bank_mask:0xf
	s_nop 0
	v_readlane_b32 s20, v180, 63
	s_nop 1
	v_mul_f32_e32 v184, s20, v2
	v_sub_f32_e32 v56, v56, v184
	v_sub_f32_e32 v57, v57, v184
	v_sub_f32_e32 v58, v58, v184
	v_sub_f32_e32 v59, v59, v184
	v_sub_f32_e32 v60, v60, v184
	v_sub_f32_e32 v61, v61, v184
	v_sub_f32_e32 v62, v62, v184
	v_sub_f32_e32 v63, v63, v184
	v_sub_f32_e32 v64, v64, v184
	v_sub_f32_e32 v65, v65, v184
	v_sub_f32_e32 v66, v66, v184
	v_sub_f32_e32 v67, v67, v184
	v_sub_f32_e32 v68, v68, v184
	v_sub_f32_e32 v69, v69, v184
	v_sub_f32_e32 v70, v70, v184
	v_sub_f32_e32 v71, v71, v184
	v_mul_f32_e32 v180, v56, v56
	v_mul_f32_e32 v181, v60, v60
	v_mul_f32_e32 v182, v64, v64
	v_mul_f32_e32 v183, v68, v68
	v_fmac_f32_e32 v180, v57, v57
	v_fmac_f32_e32 v181, v61, v61
	v_fmac_f32_e32 v182, v65, v65
	v_fmac_f32_e32 v183, v69, v69
	v_fmac_f32_e32 v180, v58, v58
	v_fmac_f32_e32 v181, v62, v62
	v_fmac_f32_e32 v182, v66, v66
	v_fmac_f32_e32 v183, v70, v70
	v_fmac_f32_e32 v180, v59, v59
	v_fmac_f32_e32 v181, v63, v63
	v_fmac_f32_e32 v182, v67, v67
	v_fmac_f32_e32 v183, v71, v71
	v_add_f32_e32 v180, v180, v181
	v_add_f32_e32 v182, v182, v183
	v_add_f32_e32 v180, v180, v182
	s_nop 1
	v_add_f32_dpp v180, v180, v180 quad_perm:[1,0,3,2] row_mask:0xf bank_mask:0xf
	s_nop 1
	v_add_f32_dpp v180, v180, v180 quad_perm:[2,3,0,1] row_mask:0xf bank_mask:0xf
	s_nop 1
	v_add_f32_dpp v180, v180, v180 row_half_mirror row_mask:0xf bank_mask:0xf
	s_nop 1
	v_add_f32_dpp v180, v180, v180 row_mirror row_mask:0xf bank_mask:0xf
	s_nop 1
	v_add_f32_dpp v180, v180, v180 row_bcast:15 row_mask:0xa bank_mask:0xf
	s_nop 1
	v_add_f32_dpp v180, v180, v180 row_bcast:31 row_mask:0xc bank_mask:0xf
	s_nop 0
	v_readlane_b32 s20, v180, 63
	s_nop 1
	v_mov_b32_e32 v185, s20
	v_fma_f32 v185, v185, v2, v4
	v_rsq_f32_e32 v185, v185
	s_nop 0
	v_mul_f32_e32 v56, v56, v185
	v_mul_f32_e32 v57, v57, v185
	v_mul_f32_e32 v58, v58, v185
	v_mul_f32_e32 v59, v59, v185
	v_mul_f32_e32 v60, v60, v185
	v_mul_f32_e32 v61, v61, v185
	v_mul_f32_e32 v62, v62, v185
	v_mul_f32_e32 v63, v63, v185
	v_mul_f32_e32 v64, v64, v185
	v_mul_f32_e32 v65, v65, v185
	v_mul_f32_e32 v66, v66, v185
	v_mul_f32_e32 v67, v67, v185
	v_mul_f32_e32 v68, v68, v185
	v_mul_f32_e32 v69, v69, v185
	v_mul_f32_e32 v70, v70, v185
	v_mul_f32_e32 v71, v71, v185
	v_fma_f32 v56, v56, v8, v24
	v_fma_f32 v57, v57, v9, v25
	v_fma_f32 v58, v58, v10, v26
	v_fma_f32 v59, v59, v11, v27
	v_fma_f32 v60, v60, v12, v28
	v_fma_f32 v61, v61, v13, v29
	v_fma_f32 v62, v62, v14, v30
	v_fma_f32 v63, v63, v15, v31
	v_fma_f32 v64, v64, v16, v32
	v_fma_f32 v65, v65, v17, v33
	v_fma_f32 v66, v66, v18, v34
	v_fma_f32 v67, v67, v19, v35
	v_fma_f32 v68, v68, v20, v36
	v_fma_f32 v69, v69, v21, v37
	v_fma_f32 v70, v70, v22, v38
	v_fma_f32 v71, v71, v23, v39
	v_add_u32_e32 v171, 0x1000, v1
	global_store_dwordx4 v171, v[56:59], s[4:5]
	global_store_dwordx4 v171, v[60:63], s[4:5] offset:1024
	global_store_dwordx4 v171, v[64:67], s[4:5] offset:2048
	global_store_dwordx4 v171, v[68:71], s[4:5] offset:3072
	s_branch .Ltr_29
.Llo_even:
	s_lshr_b32 s1, s86, 3
	s_lshl_b32 s1, s1, 6
	s_lshl_b32 s0, s0, 3
	s_add_i32 s0, s0, s1
	s_and_b32 s1, s86, 7
	s_lshl_b32 s1, s1, 11
	s_add_i32 s0, s0, s1
	s_lshl_b32 s0, s0, 12
	s_add_u32 s4, s4, s0
	s_addc_u32 s5, s5, 0
	global_load_dwordx4 v[40:43], v1, s[4:5]
	global_load_dwordx4 v[44:47], v1, s[4:5] offset:1024
	global_load_dwordx4 v[48:51], v1, s[4:5] offset:2048
	global_load_dwordx4 v[52:55], v1, s[4:5] offset:3072
	global_load_dwordx4 v[8:11], v1, s[40:41]
	global_load_dwordx4 v[12:15], v1, s[40:41] offset:1024
	global_load_dwordx4 v[16:19], v1, s[40:41] offset:2048
	global_load_dwordx4 v[20:23], v1, s[40:41] offset:3072
	global_load_dwordx4 v[24:27], v1, s[42:43]
	global_load_dwordx4 v[28:31], v1, s[42:43] offset:1024
	global_load_dwordx4 v[32:35], v1, s[42:43] offset:2048
	global_load_dwordx4 v[36:39], v1, s[42:43] offset:3072
	v_add_u32_e32 v170, 0x1000, v1
	global_load_dwordx4 v[56:59], v170, s[4:5]
	global_load_dwordx4 v[60:63], v170, s[4:5] offset:1024
	global_load_dwordx4 v[64:67], v170, s[4:5] offset:2048
	global_load_dwordx4 v[68:71], v170, s[4:5] offset:3072
	v_add_u32_e32 v170, 0x2000, v1
	global_load_dwordx4 v[72:75], v170, s[4:5]
	global_load_dwordx4 v[76:79], v170, s[4:5] offset:1024
	global_load_dwordx4 v[80:83], v170, s[4:5] offset:2048
	global_load_dwordx4 v[84:87], v170, s[4:5] offset:3072
	v_add_u32_e32 v170, 0x3000, v1
	global_load_dwordx4 v[88:91], v170, s[4:5]
	global_load_dwordx4 v[92:95], v170, s[4:5] offset:1024
	global_load_dwordx4 v[96:99], v170, s[4:5] offset:2048
	global_load_dwordx4 v[100:103], v170, s[4:5] offset:3072
	v_add_u32_e32 v170, 0x4000, v1
	global_load_dwordx4 v[104:107], v170, s[4:5]
	global_load_dwordx4 v[108:111], v170, s[4:5] offset:1024
	global_load_dwordx4 v[112:115], v170, s[4:5] offset:2048
	global_load_dwordx4 v[116:119], v170, s[4:5] offset:3072
	v_add_u32_e32 v170, 0x5000, v1
	global_load_dwordx4 v[120:123], v170, s[4:5]
	global_load_dwordx4 v[124:127], v170, s[4:5] offset:1024
	global_load_dwordx4 v[128:131], v170, s[4:5] offset:2048
	global_load_dwordx4 v[132:135], v170, s[4:5] offset:3072
	v_add_u32_e32 v170, 0x6000, v1
	global_load_dwordx4 v[136:139], v170, s[4:5]
	global_load_dwordx4 v[140:143], v170, s[4:5] offset:1024
	global_load_dwordx4 v[144:147], v170, s[4:5] offset:2048
	global_load_dwordx4 v[148:151], v170, s[4:5] offset:3072
	v_add_u32_e32 v170, 0x7000, v1
	global_load_dwordx4 v[152:155], v170, s[4:5]
	global_load_dwordx4 v[156:159], v170, s[4:5] offset:1024
	global_load_dwordx4 v[160:163], v170, s[4:5] offset:2048
	global_load_dwordx4 v[164:167], v170, s[4:5] offset:3072
	s_waitcnt vmcnt(36)
	v_add_f32_e32 v180, v40, v41
	v_add_f32_e32 v181, v44, v45
	v_add_f32_e32 v182, v48, v49
	v_add_f32_e32 v183, v52, v53
	v_add_f32_e32 v180, v180, v42
	v_add_f32_e32 v181, v181, v46
	v_add_f32_e32 v182, v182, v50
	v_add_f32_e32 v183, v183, v54
	v_add_f32_e32 v180, v180, v43
	v_add_f32_e32 v181, v181, v47
	v_add_f32_e32 v182, v182, v51
	v_add_f32_e32 v183, v183, v55
	v_add_f32_e32 v180, v180, v181
	v_add_f32_e32 v182, v182, v183
	v_add_f32_e32 v180, v180, v182
	s_nop 1
	v_add_f32_dpp v180, v180, v180 quad_perm:[1,0,3,2] row_mask:0xf bank_mask:0xf
	s_nop 1
	v_add_f32_dpp v180, v180, v180 quad_perm:[2,3,0,1] row_mask:0xf bank_mask:0xf
	s_nop 1
	v_add_f32_dpp v180, v180, v180 row_half_mirror row_mask:0xf bank_mask:0xf
	s_nop 1
	v_add_f32_dpp v180, v180, v180 row_mirror row_mask:0xf bank_mask:0xf
	s_nop 1
	v_add_f32_dpp v180, v180, v180 row_bcast:15 row_mask:0xa bank_mask:0xf
	s_nop 1
	v_add_f32_dpp v180, v180, v180 row_bcast:31 row_mask:0xc bank_mask:0xf
	s_nop 0
	v_readlane_b32 s20, v180, 63
	s_nop 1
	v_mul_f32_e32 v184, s20, v2
	v_sub_f32_e32 v40, v40, v184
	v_sub_f32_e32 v41, v41, v184
	v_sub_f32_e32 v42, v42, v184
	v_sub_f32_e32 v43, v43, v184
	v_sub_f32_e32 v44, v44, v184
	v_sub_f32_e32 v45, v45, v184
	v_sub_f32_e32 v46, v46, v184
	v_sub_f32_e32 v47, v47, v184
	v_sub_f32_e32 v48, v48, v184
	v_sub_f32_e32 v49, v49, v184
	v_sub_f32_e32 v50, v50, v184
	v_sub_f32_e32 v51, v51, v184
	v_sub_f32_e32 v52, v52, v184
	v_sub_f32_e32 v53, v53, v184
	v_sub_f32_e32 v54, v54, v184
	v_sub_f32_e32 v55, v55, v184
	v_mul_f32_e32 v180, v40, v40
	v_mul_f32_e32 v181, v44, v44
	v_mul_f32_e32 v182, v48, v48
	v_mul_f32_e32 v183, v52, v52
	v_fmac_f32_e32 v180, v41, v41
	v_fmac_f32_e32 v181, v45, v45
	v_fmac_f32_e32 v182, v49, v49
	v_fmac_f32_e32 v183, v53, v53
	v_fmac_f32_e32 v180, v42, v42
	v_fmac_f32_e32 v181, v46, v46
	v_fmac_f32_e32 v182, v50, v50
	v_fmac_f32_e32 v183, v54, v54
	v_fmac_f32_e32 v180, v43, v43
	v_fmac_f32_e32 v181, v47, v47
	v_fmac_f32_e32 v182, v51, v51
	v_fmac_f32_e32 v183, v55, v55
	v_add_f32_e32 v180, v180, v181
	v_add_f32_e32 v182, v182, v183
	v_add_f32_e32 v180, v180, v182
	s_nop 1
	v_add_f32_dpp v180, v180, v180 quad_perm:[1,0,3,2] row_mask:0xf bank_mask:0xf
	s_nop 1
	v_add_f32_dpp v180, v180, v180 quad_perm:[2,3,0,1] row_mask:0xf bank_mask:0xf
	s_nop 1
	v_add_f32_dpp v180, v180, v180 row_half_mirror row_mask:0xf bank_mask:0xf
	s_nop 1
	v_add_f32_dpp v180, v180, v180 row_mirror row_mask:0xf bank_mask:0xf
	s_nop 1
	v_add_f32_dpp v180, v180, v180 row_bcast:15 row_mask:0xa bank_mask:0xf
	s_nop 1
	v_add_f32_dpp v180, v180, v180 row_bcast:31 row_mask:0xc bank_mask:0xf
	s_nop 0
	v_readlane_b32 s20, v180, 63
	s_nop 1
	v_mov_b32_e32 v185, s20
	v_fma_f32 v185, v185, v2, v4
	v_rsq_f32_e32 v185, v185
	s_nop 0
	v_mul_f32_e32 v40, v40, v185
	v_mul_f32_e32 v41, v41, v185
	v_mul_f32_e32 v42, v42, v185
	v_mul_f32_e32 v43, v43, v185
	v_mul_f32_e32 v44, v44, v185
	v_mul_f32_e32 v45, v45, v185
	v_mul_f32_e32 v46, v46, v185
	v_mul_f32_e32 v47, v47, v185
	v_mul_f32_e32 v48, v48, v185
	v_mul_f32_e32 v49, v49, v185
	v_mul_f32_e32 v50, v50, v185
	v_mul_f32_e32 v51, v51, v185
	v_mul_f32_e32 v52, v52, v185
	v_mul_f32_e32 v53, v53, v185
	v_mul_f32_e32 v54, v54, v185
	v_mul_f32_e32 v55, v55, v185
	s_waitcnt vmcnt(28)
	v_fma_f32 v40, v40, v8, v24
	v_fma_f32 v41, v41, v9, v25
	v_fma_f32 v42, v42, v10, v26
	v_fma_f32 v43, v43, v11, v27
	v_fma_f32 v44, v44, v12, v28
	v_fma_f32 v45, v45, v13, v29
	v_fma_f32 v46, v46, v14, v30
	v_fma_f32 v47, v47, v15, v31
	v_fma_f32 v48, v48, v16, v32
	v_fma_f32 v49, v49, v17, v33
	v_fma_f32 v50, v50, v18, v34
	v_fma_f32 v51, v51, v19, v35
	v_fma_f32 v52, v52, v20, v36
	v_fma_f32 v53, v53, v21, v37
	v_fma_f32 v54, v54, v22, v38
	v_fma_f32 v55, v55, v23, v39
	global_store_dwordx4 v1, v[40:43], s[4:5]
	global_store_dwordx4 v1, v[44:47], s[4:5] offset:1024
	global_store_dwordx4 v1, v[48:51], s[4:5] offset:2048
	global_store_dwordx4 v1, v[52:55], s[4:5] offset:3072
	s_waitcnt vmcnt(28)
	v_add_f32_e32 v180, v56, v57
	v_add_f32_e32 v181, v60, v61
	v_add_f32_e32 v182, v64, v65
	v_add_f32_e32 v183, v68, v69
	v_add_f32_e32 v180, v180, v58
	v_add_f32_e32 v181, v181, v62
	v_add_f32_e32 v182, v182, v66
	v_add_f32_e32 v183, v183, v70
	v_add_f32_e32 v180, v180, v59
	v_add_f32_e32 v181, v181, v63
	v_add_f32_e32 v182, v182, v67
	v_add_f32_e32 v183, v183, v71
	v_add_f32_e32 v180, v180, v181
	v_add_f32_e32 v182, v182, v183
	v_add_f32_e32 v180, v180, v182
	s_nop 1
	v_add_f32_dpp v180, v180, v180 quad_perm:[1,0,3,2] row_mask:0xf bank_mask:0xf
	s_nop 1
	v_add_f32_dpp v180, v180, v180 quad_perm:[2,3,0,1] row_mask:0xf bank_mask:0xf
	s_nop 1
	v_add_f32_dpp v180, v180, v180 row_half_mirror row_mask:0xf bank_mask:0xf
	s_nop 1
	v_add_f32_dpp v180, v180, v180 row_mirror row_mask:0xf bank_mask:0xf
	s_nop 1
	v_add_f32_dpp v180, v180, v180 row_bcast:15 row_mask:0xa bank_mask:0xf
	s_nop 1
	v_add_f32_dpp v180, v180, v180 row_bcast:31 row_mask:0xc bank_mask:0xf
	s_nop 0
	v_readlane_b32 s20, v180, 63
	s_nop 1
	v_mul_f32_e32 v184, s20, v2
	v_sub_f32_e32 v56, v56, v184
	v_sub_f32_e32 v57, v57, v184
	v_sub_f32_e32 v58, v58, v184
	v_sub_f32_e32 v59, v59, v184
	v_sub_f32_e32 v60, v60, v184
	v_sub_f32_e32 v61, v61, v184
	v_sub_f32_e32 v62, v62, v184
	v_sub_f32_e32 v63, v63, v184
	v_sub_f32_e32 v64, v64, v184
	v_sub_f32_e32 v65, v65, v184
	v_sub_f32_e32 v66, v66, v184
	v_sub_f32_e32 v67, v67, v184
	v_sub_f32_e32 v68, v68, v184
	v_sub_f32_e32 v69, v69, v184
	v_sub_f32_e32 v70, v70, v184
	v_sub_f32_e32 v71, v71, v184
	v_mul_f32_e32 v180, v56, v56
	v_mul_f32_e32 v181, v60, v60
	v_mul_f32_e32 v182, v64, v64
	v_mul_f32_e32 v183, v68, v68
	v_fmac_f32_e32 v180, v57, v57
	v_fmac_f32_e32 v181, v61, v61
	v_fmac_f32_e32 v182, v65, v65
	v_fmac_f32_e32 v183, v69, v69
	v_fmac_f32_e32 v180, v58, v58
	v_fmac_f32_e32 v181, v62, v62
	v_fmac_f32_e32 v182, v66, v66
	v_fmac_f32_e32 v183, v70, v70
	v_fmac_f32_e32 v180, v59, v59
	v_fmac_f32_e32 v181, v63, v63
	v_fmac_f32_e32 v182, v67, v67
	v_fmac_f32_e32 v183, v71, v71
	v_add_f32_e32 v180, v180, v181
	v_add_f32_e32 v182, v182, v183
	v_add_f32_e32 v180, v180, v182
	s_nop 1
	v_add_f32_dpp v180, v180, v180 quad_perm:[1,0,3,2] row_mask:0xf bank_mask:0xf
	s_nop 1
	v_add_f32_dpp v180, v180, v180 quad_perm:[2,3,0,1] row_mask:0xf bank_mask:0xf
	s_nop 1
	v_add_f32_dpp v180, v180, v180 row_half_mirror row_mask:0xf bank_mask:0xf
	s_nop 1
	v_add_f32_dpp v180, v180, v180 row_mirror row_mask:0xf bank_mask:0xf
	s_nop 1
	v_add_f32_dpp v180, v180, v180 row_bcast:15 row_mask:0xa bank_mask:0xf
	s_nop 1
	v_add_f32_dpp v180, v180, v180 row_bcast:31 row_mask:0xc bank_mask:0xf
	s_nop 0
	v_readlane_b32 s20, v180, 63
	s_nop 1
	v_mov_b32_e32 v185, s20
	v_fma_f32 v185, v185, v2, v4
	v_rsq_f32_e32 v185, v185
	s_nop 0
	v_mul_f32_e32 v56, v56, v185
	v_mul_f32_e32 v57, v57, v185
	v_mul_f32_e32 v58, v58, v185
	v_mul_f32_e32 v59, v59, v185
	v_mul_f32_e32 v60, v60, v185
	v_mul_f32_e32 v61, v61, v185
	v_mul_f32_e32 v62, v62, v185
	v_mul_f32_e32 v63, v63, v185
	v_mul_f32_e32 v64, v64, v185
	v_mul_f32_e32 v65, v65, v185
	v_mul_f32_e32 v66, v66, v185
	v_mul_f32_e32 v67, v67, v185
	v_mul_f32_e32 v68, v68, v185
	v_mul_f32_e32 v69, v69, v185
	v_mul_f32_e32 v70, v70, v185
	v_mul_f32_e32 v71, v71, v185
	v_fma_f32 v56, v56, v8, v24
	v_fma_f32 v57, v57, v9, v25
	v_fma_f32 v58, v58, v10, v26
	v_fma_f32 v59, v59, v11, v27
	v_fma_f32 v60, v60, v12, v28
	v_fma_f32 v61, v61, v13, v29
	v_fma_f32 v62, v62, v14, v30
	v_fma_f32 v63, v63, v15, v31
	v_fma_f32 v64, v64, v16, v32
	v_fma_f32 v65, v65, v17, v33
	v_fma_f32 v66, v66, v18, v34
	v_fma_f32 v67, v67, v19, v35
	v_fma_f32 v68, v68, v20, v36
	v_fma_f32 v69, v69, v21, v37
	v_fma_f32 v70, v70, v22, v38
	v_fma_f32 v71, v71, v23, v39
	v_add_u32_e32 v171, 0x1000, v1
	global_store_dwordx4 v171, v[56:59], s[4:5]
	global_store_dwordx4 v171, v[60:63], s[4:5] offset:1024
	global_store_dwordx4 v171, v[64:67], s[4:5] offset:2048
	global_store_dwordx4 v171, v[68:71], s[4:5] offset:3072
	s_waitcnt vmcnt(28)
	v_add_f32_e32 v180, v72, v73
	v_add_f32_e32 v181, v76, v77
	v_add_f32_e32 v182, v80, v81
	v_add_f32_e32 v183, v84, v85
	v_add_f32_e32 v180, v180, v74
	v_add_f32_e32 v181, v181, v78
	v_add_f32_e32 v182, v182, v82
	v_add_f32_e32 v183, v183, v86
	v_add_f32_e32 v180, v180, v75
	v_add_f32_e32 v181, v181, v79
	v_add_f32_e32 v182, v182, v83
	v_add_f32_e32 v183, v183, v87
	v_add_f32_e32 v180, v180, v181
	v_add_f32_e32 v182, v182, v183
	v_add_f32_e32 v180, v180, v182
	s_nop 1
	v_add_f32_dpp v180, v180, v180 quad_perm:[1,0,3,2] row_mask:0xf bank_mask:0xf
	s_nop 1
	v_add_f32_dpp v180, v180, v180 quad_perm:[2,3,0,1] row_mask:0xf bank_mask:0xf
	s_nop 1
	v_add_f32_dpp v180, v180, v180 row_half_mirror row_mask:0xf bank_mask:0xf
	s_nop 1
	v_add_f32_dpp v180, v180, v180 row_mirror row_mask:0xf bank_mask:0xf
	s_nop 1
	v_add_f32_dpp v180, v180, v180 row_bcast:15 row_mask:0xa bank_mask:0xf
	s_nop 1
	v_add_f32_dpp v180, v180, v180 row_bcast:31 row_mask:0xc bank_mask:0xf
	s_nop 0
	v_readlane_b32 s20, v180, 63
	s_nop 1
	v_mul_f32_e32 v184, s20, v2
	v_sub_f32_e32 v72, v72, v184
	v_sub_f32_e32 v73, v73, v184
	v_sub_f32_e32 v74, v74, v184
	v_sub_f32_e32 v75, v75, v184
	v_sub_f32_e32 v76, v76, v184
	v_sub_f32_e32 v77, v77, v184
	v_sub_f32_e32 v78, v78, v184
	v_sub_f32_e32 v79, v79, v184
	v_sub_f32_e32 v80, v80, v184
	v_sub_f32_e32 v81, v81, v184
	v_sub_f32_e32 v82, v82, v184
	v_sub_f32_e32 v83, v83, v184
	v_sub_f32_e32 v84, v84, v184
	v_sub_f32_e32 v85, v85, v184
	v_sub_f32_e32 v86, v86, v184
	v_sub_f32_e32 v87, v87, v184
	v_mul_f32_e32 v180, v72, v72
	v_mul_f32_e32 v181, v76, v76
	v_mul_f32_e32 v182, v80, v80
	v_mul_f32_e32 v183, v84, v84
	v_fmac_f32_e32 v180, v73, v73
	v_fmac_f32_e32 v181, v77, v77
	v_fmac_f32_e32 v182, v81, v81
	v_fmac_f32_e32 v183, v85, v85
	v_fmac_f32_e32 v180, v74, v74
	v_fmac_f32_e32 v181, v78, v78
	v_fmac_f32_e32 v182, v82, v82
	v_fmac_f32_e32 v183, v86, v86
	v_fmac_f32_e32 v180, v75, v75
	v_fmac_f32_e32 v181, v79, v79
	v_fmac_f32_e32 v182, v83, v83
	v_fmac_f32_e32 v183, v87, v87
	v_add_f32_e32 v180, v180, v181
	v_add_f32_e32 v182, v182, v183
	v_add_f32_e32 v180, v180, v182
	s_nop 1
	v_add_f32_dpp v180, v180, v180 quad_perm:[1,0,3,2] row_mask:0xf bank_mask:0xf
	s_nop 1
	v_add_f32_dpp v180, v180, v180 quad_perm:[2,3,0,1] row_mask:0xf bank_mask:0xf
	s_nop 1
	v_add_f32_dpp v180, v180, v180 row_half_mirror row_mask:0xf bank_mask:0xf
	s_nop 1
	v_add_f32_dpp v180, v180, v180 row_mirror row_mask:0xf bank_mask:0xf
	s_nop 1
	v_add_f32_dpp v180, v180, v180 row_bcast:15 row_mask:0xa bank_mask:0xf
	s_nop 1
	v_add_f32_dpp v180, v180, v180 row_bcast:31 row_mask:0xc bank_mask:0xf
	s_nop 0
	v_readlane_b32 s20, v180, 63
	s_nop 1
	v_mov_b32_e32 v185, s20
	v_fma_f32 v185, v185, v2, v4
	v_rsq_f32_e32 v185, v185
	s_nop 0
	v_mul_f32_e32 v72, v72, v185
	v_mul_f32_e32 v73, v73, v185
	v_mul_f32_e32 v74, v74, v185
	v_mul_f32_e32 v75, v75, v185
	v_mul_f32_e32 v76, v76, v185
	v_mul_f32_e32 v77, v77, v185
	v_mul_f32_e32 v78, v78, v185
	v_mul_f32_e32 v79, v79, v185
	v_mul_f32_e32 v80, v80, v185
	v_mul_f32_e32 v81, v81, v185
	v_mul_f32_e32 v82, v82, v185
	v_mul_f32_e32 v83, v83, v185
	v_mul_f32_e32 v84, v84, v185
	v_mul_f32_e32 v85, v85, v185
	v_mul_f32_e32 v86, v86, v185
	v_mul_f32_e32 v87, v87, v185
	v_fma_f32 v72, v72, v8, v24
	v_fma_f32 v73, v73, v9, v25
	v_fma_f32 v74, v74, v10, v26
	v_fma_f32 v75, v75, v11, v27
	v_fma_f32 v76, v76, v12, v28
	v_fma_f32 v77, v77, v13, v29
	v_fma_f32 v78, v78, v14, v30
	v_fma_f32 v79, v79, v15, v31
	v_fma_f32 v80, v80, v16, v32
	v_fma_f32 v81, v81, v17, v33
	v_fma_f32 v82, v82, v18, v34
	v_fma_f32 v83, v83, v19, v35
	v_fma_f32 v84, v84, v20, v36
	v_fma_f32 v85, v85, v21, v37
	v_fma_f32 v86, v86, v22, v38
	v_fma_f32 v87, v87, v23, v39
	v_add_u32_e32 v171, 0x2000, v1
	global_store_dwordx4 v171, v[72:75], s[4:5]
	global_store_dwordx4 v171, v[76:79], s[4:5] offset:1024
	global_store_dwordx4 v171, v[80:83], s[4:5] offset:2048
	global_store_dwordx4 v171, v[84:87], s[4:5] offset:3072
	s_waitcnt vmcnt(28)
	v_add_f32_e32 v180, v88, v89
	v_add_f32_e32 v181, v92, v93
	v_add_f32_e32 v182, v96, v97
	v_add_f32_e32 v183, v100, v101
	v_add_f32_e32 v180, v180, v90
	v_add_f32_e32 v181, v181, v94
	v_add_f32_e32 v182, v182, v98
	v_add_f32_e32 v183, v183, v102
	v_add_f32_e32 v180, v180, v91
	v_add_f32_e32 v181, v181, v95
	v_add_f32_e32 v182, v182, v99
	v_add_f32_e32 v183, v183, v103
	v_add_f32_e32 v180, v180, v181
	v_add_f32_e32 v182, v182, v183
	v_add_f32_e32 v180, v180, v182
	s_nop 1
	v_add_f32_dpp v180, v180, v180 quad_perm:[1,0,3,2] row_mask:0xf bank_mask:0xf
	s_nop 1
	v_add_f32_dpp v180, v180, v180 quad_perm:[2,3,0,1] row_mask:0xf bank_mask:0xf
	s_nop 1
	v_add_f32_dpp v180, v180, v180 row_half_mirror row_mask:0xf bank_mask:0xf
	s_nop 1
	v_add_f32_dpp v180, v180, v180 row_mirror row_mask:0xf bank_mask:0xf
	s_nop 1
	v_add_f32_dpp v180, v180, v180 row_bcast:15 row_mask:0xa bank_mask:0xf
	s_nop 1
	v_add_f32_dpp v180, v180, v180 row_bcast:31 row_mask:0xc bank_mask:0xf
	s_nop 0
	v_readlane_b32 s20, v180, 63
	s_nop 1
	v_mul_f32_e32 v184, s20, v2
	v_sub_f32_e32 v88, v88, v184
	v_sub_f32_e32 v89, v89, v184
	v_sub_f32_e32 v90, v90, v184
	v_sub_f32_e32 v91, v91, v184
	v_sub_f32_e32 v92, v92, v184
	v_sub_f32_e32 v93, v93, v184
	v_sub_f32_e32 v94, v94, v184
	v_sub_f32_e32 v95, v95, v184
	v_sub_f32_e32 v96, v96, v184
	v_sub_f32_e32 v97, v97, v184
	v_sub_f32_e32 v98, v98, v184
	v_sub_f32_e32 v99, v99, v184
	v_sub_f32_e32 v100, v100, v184
	v_sub_f32_e32 v101, v101, v184
	v_sub_f32_e32 v102, v102, v184
	v_sub_f32_e32 v103, v103, v184
	v_mul_f32_e32 v180, v88, v88
	v_mul_f32_e32 v181, v92, v92
	v_mul_f32_e32 v182, v96, v96
	v_mul_f32_e32 v183, v100, v100
	v_fmac_f32_e32 v180, v89, v89
	v_fmac_f32_e32 v181, v93, v93
	v_fmac_f32_e32 v182, v97, v97
	v_fmac_f32_e32 v183, v101, v101
	v_fmac_f32_e32 v180, v90, v90
	v_fmac_f32_e32 v181, v94, v94
	v_fmac_f32_e32 v182, v98, v98
	v_fmac_f32_e32 v183, v102, v102
	v_fmac_f32_e32 v180, v91, v91
	v_fmac_f32_e32 v181, v95, v95
	v_fmac_f32_e32 v182, v99, v99
	v_fmac_f32_e32 v183, v103, v103
	v_add_f32_e32 v180, v180, v181
	v_add_f32_e32 v182, v182, v183
	v_add_f32_e32 v180, v180, v182
	s_nop 1
	v_add_f32_dpp v180, v180, v180 quad_perm:[1,0,3,2] row_mask:0xf bank_mask:0xf
	s_nop 1
	v_add_f32_dpp v180, v180, v180 quad_perm:[2,3,0,1] row_mask:0xf bank_mask:0xf
	s_nop 1
	v_add_f32_dpp v180, v180, v180 row_half_mirror row_mask:0xf bank_mask:0xf
	s_nop 1
	v_add_f32_dpp v180, v180, v180 row_mirror row_mask:0xf bank_mask:0xf
	s_nop 1
	v_add_f32_dpp v180, v180, v180 row_bcast:15 row_mask:0xa bank_mask:0xf
	s_nop 1
	v_add_f32_dpp v180, v180, v180 row_bcast:31 row_mask:0xc bank_mask:0xf
	s_nop 0
	v_readlane_b32 s20, v180, 63
	s_nop 1
	v_mov_b32_e32 v185, s20
	v_fma_f32 v185, v185, v2, v4
	v_rsq_f32_e32 v185, v185
	s_nop 0
	v_mul_f32_e32 v88, v88, v185
	v_mul_f32_e32 v89, v89, v185
	v_mul_f32_e32 v90, v90, v185
	v_mul_f32_e32 v91, v91, v185
	v_mul_f32_e32 v92, v92, v185
	v_mul_f32_e32 v93, v93, v185
	v_mul_f32_e32 v94, v94, v185
	v_mul_f32_e32 v95, v95, v185
	v_mul_f32_e32 v96, v96, v185
	v_mul_f32_e32 v97, v97, v185
	v_mul_f32_e32 v98, v98, v185
	v_mul_f32_e32 v99, v99, v185
	v_mul_f32_e32 v100, v100, v185
	v_mul_f32_e32 v101, v101, v185
	v_mul_f32_e32 v102, v102, v185
	v_mul_f32_e32 v103, v103, v185
	v_fma_f32 v88, v88, v8, v24
	v_fma_f32 v89, v89, v9, v25
	v_fma_f32 v90, v90, v10, v26
	v_fma_f32 v91, v91, v11, v27
	v_fma_f32 v92, v92, v12, v28
	v_fma_f32 v93, v93, v13, v29
	v_fma_f32 v94, v94, v14, v30
	v_fma_f32 v95, v95, v15, v31
	v_fma_f32 v96, v96, v16, v32
	v_fma_f32 v97, v97, v17, v33
	v_fma_f32 v98, v98, v18, v34
	v_fma_f32 v99, v99, v19, v35
	v_fma_f32 v100, v100, v20, v36
	v_fma_f32 v101, v101, v21, v37
	v_fma_f32 v102, v102, v22, v38
	v_fma_f32 v103, v103, v23, v39
	v_add_u32_e32 v171, 0x3000, v1
	global_store_dwordx4 v171, v[88:91], s[4:5]
	global_store_dwordx4 v171, v[92:95], s[4:5] offset:1024
	global_store_dwordx4 v171, v[96:99], s[4:5] offset:2048
	global_store_dwordx4 v171, v[100:103], s[4:5] offset:3072
	s_waitcnt vmcnt(28)
	v_add_f32_e32 v180, v104, v105
	v_add_f32_e32 v181, v108, v109
	v_add_f32_e32 v182, v112, v113
	v_add_f32_e32 v183, v116, v117
	v_add_f32_e32 v180, v180, v106
	v_add_f32_e32 v181, v181, v110
	v_add_f32_e32 v182, v182, v114
	v_add_f32_e32 v183, v183, v118
	v_add_f32_e32 v180, v180, v107
	v_add_f32_e32 v181, v181, v111
	v_add_f32_e32 v182, v182, v115
	v_add_f32_e32 v183, v183, v119
	v_add_f32_e32 v180, v180, v181
	v_add_f32_e32 v182, v182, v183
	v_add_f32_e32 v180, v180, v182
	s_nop 1
	v_add_f32_dpp v180, v180, v180 quad_perm:[1,0,3,2] row_mask:0xf bank_mask:0xf
	s_nop 1
	v_add_f32_dpp v180, v180, v180 quad_perm:[2,3,0,1] row_mask:0xf bank_mask:0xf
	s_nop 1
	v_add_f32_dpp v180, v180, v180 row_half_mirror row_mask:0xf bank_mask:0xf
	s_nop 1
	v_add_f32_dpp v180, v180, v180 row_mirror row_mask:0xf bank_mask:0xf
	s_nop 1
	v_add_f32_dpp v180, v180, v180 row_bcast:15 row_mask:0xa bank_mask:0xf
	s_nop 1
	v_add_f32_dpp v180, v180, v180 row_bcast:31 row_mask:0xc bank_mask:0xf
	s_nop 0
	v_readlane_b32 s20, v180, 63
	s_nop 1
	v_mul_f32_e32 v184, s20, v2
	v_sub_f32_e32 v104, v104, v184
	v_sub_f32_e32 v105, v105, v184
	v_sub_f32_e32 v106, v106, v184
	v_sub_f32_e32 v107, v107, v184
	v_sub_f32_e32 v108, v108, v184
	v_sub_f32_e32 v109, v109, v184
	v_sub_f32_e32 v110, v110, v184
	v_sub_f32_e32 v111, v111, v184
	v_sub_f32_e32 v112, v112, v184
	v_sub_f32_e32 v113, v113, v184
	v_sub_f32_e32 v114, v114, v184
	v_sub_f32_e32 v115, v115, v184
	v_sub_f32_e32 v116, v116, v184
	v_sub_f32_e32 v117, v117, v184
	v_sub_f32_e32 v118, v118, v184
	v_sub_f32_e32 v119, v119, v184
	v_mul_f32_e32 v180, v104, v104
	v_mul_f32_e32 v181, v108, v108
	v_mul_f32_e32 v182, v112, v112
	v_mul_f32_e32 v183, v116, v116
	v_fmac_f32_e32 v180, v105, v105
	v_fmac_f32_e32 v181, v109, v109
	v_fmac_f32_e32 v182, v113, v113
	v_fmac_f32_e32 v183, v117, v117
	v_fmac_f32_e32 v180, v106, v106
	v_fmac_f32_e32 v181, v110, v110
	v_fmac_f32_e32 v182, v114, v114
	v_fmac_f32_e32 v183, v118, v118
	v_fmac_f32_e32 v180, v107, v107
	v_fmac_f32_e32 v181, v111, v111
	v_fmac_f32_e32 v182, v115, v115
	v_fmac_f32_e32 v183, v119, v119
	v_add_f32_e32 v180, v180, v181
	v_add_f32_e32 v182, v182, v183
	v_add_f32_e32 v180, v180, v182
	s_nop 1
	v_add_f32_dpp v180, v180, v180 quad_perm:[1,0,3,2] row_mask:0xf bank_mask:0xf
	s_nop 1
	v_add_f32_dpp v180, v180, v180 quad_perm:[2,3,0,1] row_mask:0xf bank_mask:0xf
	s_nop 1
	v_add_f32_dpp v180, v180, v180 row_half_mirror row_mask:0xf bank_mask:0xf
	s_nop 1
	v_add_f32_dpp v180, v180, v180 row_mirror row_mask:0xf bank_mask:0xf
	s_nop 1
	v_add_f32_dpp v180, v180, v180 row_bcast:15 row_mask:0xa bank_mask:0xf
	s_nop 1
	v_add_f32_dpp v180, v180, v180 row_bcast:31 row_mask:0xc bank_mask:0xf
	s_nop 0
	v_readlane_b32 s20, v180, 63
	s_nop 1
	v_mov_b32_e32 v185, s20
	v_fma_f32 v185, v185, v2, v4
	v_rsq_f32_e32 v185, v185
	s_nop 0
	v_mul_f32_e32 v104, v104, v185
	v_mul_f32_e32 v105, v105, v185
	v_mul_f32_e32 v106, v106, v185
	v_mul_f32_e32 v107, v107, v185
	v_mul_f32_e32 v108, v108, v185
	v_mul_f32_e32 v109, v109, v185
	v_mul_f32_e32 v110, v110, v185
	v_mul_f32_e32 v111, v111, v185
	v_mul_f32_e32 v112, v112, v185
	v_mul_f32_e32 v113, v113, v185
	v_mul_f32_e32 v114, v114, v185
	v_mul_f32_e32 v115, v115, v185
	v_mul_f32_e32 v116, v116, v185
	v_mul_f32_e32 v117, v117, v185
	v_mul_f32_e32 v118, v118, v185
	v_mul_f32_e32 v119, v119, v185
	v_fma_f32 v104, v104, v8, v24
	v_fma_f32 v105, v105, v9, v25
	v_fma_f32 v106, v106, v10, v26
	v_fma_f32 v107, v107, v11, v27
	v_fma_f32 v108, v108, v12, v28
	v_fma_f32 v109, v109, v13, v29
	v_fma_f32 v110, v110, v14, v30
	v_fma_f32 v111, v111, v15, v31
	v_fma_f32 v112, v112, v16, v32
	v_fma_f32 v113, v113, v17, v33
	v_fma_f32 v114, v114, v18, v34
	v_fma_f32 v115, v115, v19, v35
	v_fma_f32 v116, v116, v20, v36
	v_fma_f32 v117, v117, v21, v37
	v_fma_f32 v118, v118, v22, v38
	v_fma_f32 v119, v119, v23, v39
	v_add_u32_e32 v171, 0x4000, v1
	global_store_dwordx4 v171, v[104:107], s[4:5]
	global_store_dwordx4 v171, v[108:111], s[4:5] offset:1024
	global_store_dwordx4 v171, v[112:115], s[4:5] offset:2048
	global_store_dwordx4 v171, v[116:119], s[4:5] offset:3072
	s_waitcnt vmcnt(28)
	v_add_f32_e32 v180, v120, v121
	v_add_f32_e32 v181, v124, v125
	v_add_f32_e32 v182, v128, v129
	v_add_f32_e32 v183, v132, v133
	v_add_f32_e32 v180, v180, v122
	v_add_f32_e32 v181, v181, v126
	v_add_f32_e32 v182, v182, v130
	v_add_f32_e32 v183, v183, v134
	v_add_f32_e32 v180, v180, v123
	v_add_f32_e32 v181, v181, v127
	v_add_f32_e32 v182, v182, v131
	v_add_f32_e32 v183, v183, v135
	v_add_f32_e32 v180, v180, v181
	v_add_f32_e32 v182, v182, v183
	v_add_f32_e32 v180, v180, v182
	s_nop 1
	v_add_f32_dpp v180, v180, v180 quad_perm:[1,0,3,2] row_mask:0xf bank_mask:0xf
	s_nop 1
	v_add_f32_dpp v180, v180, v180 quad_perm:[2,3,0,1] row_mask:0xf bank_mask:0xf
	s_nop 1
	v_add_f32_dpp v180, v180, v180 row_half_mirror row_mask:0xf bank_mask:0xf
	s_nop 1
	v_add_f32_dpp v180, v180, v180 row_mirror row_mask:0xf bank_mask:0xf
	s_nop 1
	v_add_f32_dpp v180, v180, v180 row_bcast:15 row_mask:0xa bank_mask:0xf
	s_nop 1
	v_add_f32_dpp v180, v180, v180 row_bcast:31 row_mask:0xc bank_mask:0xf
	s_nop 0
	v_readlane_b32 s20, v180, 63
	s_nop 1
	v_mul_f32_e32 v184, s20, v2
	v_sub_f32_e32 v120, v120, v184
	v_sub_f32_e32 v121, v121, v184
	v_sub_f32_e32 v122, v122, v184
	v_sub_f32_e32 v123, v123, v184
	v_sub_f32_e32 v124, v124, v184
	v_sub_f32_e32 v125, v125, v184
	v_sub_f32_e32 v126, v126, v184
	v_sub_f32_e32 v127, v127, v184
	v_sub_f32_e32 v128, v128, v184
	v_sub_f32_e32 v129, v129, v184
	v_sub_f32_e32 v130, v130, v184
	v_sub_f32_e32 v131, v131, v184
	v_sub_f32_e32 v132, v132, v184
	v_sub_f32_e32 v133, v133, v184
	v_sub_f32_e32 v134, v134, v184
	v_sub_f32_e32 v135, v135, v184
	v_mul_f32_e32 v180, v120, v120
	v_mul_f32_e32 v181, v124, v124
	v_mul_f32_e32 v182, v128, v128
	v_mul_f32_e32 v183, v132, v132
	v_fmac_f32_e32 v180, v121, v121
	v_fmac_f32_e32 v181, v125, v125
	v_fmac_f32_e32 v182, v129, v129
	v_fmac_f32_e32 v183, v133, v133
	v_fmac_f32_e32 v180, v122, v122
	v_fmac_f32_e32 v181, v126, v126
	v_fmac_f32_e32 v182, v130, v130
	v_fmac_f32_e32 v183, v134, v134
	v_fmac_f32_e32 v180, v123, v123
	v_fmac_f32_e32 v181, v127, v127
	v_fmac_f32_e32 v182, v131, v131
	v_fmac_f32_e32 v183, v135, v135
	v_add_f32_e32 v180, v180, v181
	v_add_f32_e32 v182, v182, v183
	v_add_f32_e32 v180, v180, v182
	s_nop 1
	v_add_f32_dpp v180, v180, v180 quad_perm:[1,0,3,2] row_mask:0xf bank_mask:0xf
	s_nop 1
	v_add_f32_dpp v180, v180, v180 quad_perm:[2,3,0,1] row_mask:0xf bank_mask:0xf
	s_nop 1
	v_add_f32_dpp v180, v180, v180 row_half_mirror row_mask:0xf bank_mask:0xf
	s_nop 1
	v_add_f32_dpp v180, v180, v180 row_mirror row_mask:0xf bank_mask:0xf
	s_nop 1
	v_add_f32_dpp v180, v180, v180 row_bcast:15 row_mask:0xa bank_mask:0xf
	s_nop 1
	v_add_f32_dpp v180, v180, v180 row_bcast:31 row_mask:0xc bank_mask:0xf
	s_nop 0
	v_readlane_b32 s20, v180, 63
	s_nop 1
	v_mov_b32_e32 v185, s20
	v_fma_f32 v185, v185, v2, v4
	v_rsq_f32_e32 v185, v185
	s_nop 0
	v_mul_f32_e32 v120, v120, v185
	v_mul_f32_e32 v121, v121, v185
	v_mul_f32_e32 v122, v122, v185
	v_mul_f32_e32 v123, v123, v185
	v_mul_f32_e32 v124, v124, v185
	v_mul_f32_e32 v125, v125, v185
	v_mul_f32_e32 v126, v126, v185
	v_mul_f32_e32 v127, v127, v185
	v_mul_f32_e32 v128, v128, v185
	v_mul_f32_e32 v129, v129, v185
	v_mul_f32_e32 v130, v130, v185
	v_mul_f32_e32 v131, v131, v185
	v_mul_f32_e32 v132, v132, v185
	v_mul_f32_e32 v133, v133, v185
	v_mul_f32_e32 v134, v134, v185
	v_mul_f32_e32 v135, v135, v185
	v_fma_f32 v120, v120, v8, v24
	v_fma_f32 v121, v121, v9, v25
	v_fma_f32 v122, v122, v10, v26
	v_fma_f32 v123, v123, v11, v27
	v_fma_f32 v124, v124, v12, v28
	v_fma_f32 v125, v125, v13, v29
	v_fma_f32 v126, v126, v14, v30
	v_fma_f32 v127, v127, v15, v31
	v_fma_f32 v128, v128, v16, v32
	v_fma_f32 v129, v129, v17, v33
	v_fma_f32 v130, v130, v18, v34
	v_fma_f32 v131, v131, v19, v35
	v_fma_f32 v132, v132, v20, v36
	v_fma_f32 v133, v133, v21, v37
	v_fma_f32 v134, v134, v22, v38
	v_fma_f32 v135, v135, v23, v39
	v_add_u32_e32 v171, 0x5000, v1
	global_store_dwordx4 v171, v[120:123], s[4:5]
	global_store_dwordx4 v171, v[124:127], s[4:5] offset:1024
	global_store_dwordx4 v171, v[128:131], s[4:5] offset:2048
	global_store_dwordx4 v171, v[132:135], s[4:5] offset:3072
	s_waitcnt vmcnt(28)
	v_add_f32_e32 v180, v136, v137
	v_add_f32_e32 v181, v140, v141
	v_add_f32_e32 v182, v144, v145
	v_add_f32_e32 v183, v148, v149
	v_add_f32_e32 v180, v180, v138
	v_add_f32_e32 v181, v181, v142
	v_add_f32_e32 v182, v182, v146
	v_add_f32_e32 v183, v183, v150
	v_add_f32_e32 v180, v180, v139
	v_add_f32_e32 v181, v181, v143
	v_add_f32_e32 v182, v182, v147
	v_add_f32_e32 v183, v183, v151
	v_add_f32_e32 v180, v180, v181
	v_add_f32_e32 v182, v182, v183
	v_add_f32_e32 v180, v180, v182
	s_nop 1
	v_add_f32_dpp v180, v180, v180 quad_perm:[1,0,3,2] row_mask:0xf bank_mask:0xf
	s_nop 1
	v_add_f32_dpp v180, v180, v180 quad_perm:[2,3,0,1] row_mask:0xf bank_mask:0xf
	s_nop 1
	v_add_f32_dpp v180, v180, v180 row_half_mirror row_mask:0xf bank_mask:0xf
	s_nop 1
	v_add_f32_dpp v180, v180, v180 row_mirror row_mask:0xf bank_mask:0xf
	s_nop 1
	v_add_f32_dpp v180, v180, v180 row_bcast:15 row_mask:0xa bank_mask:0xf
	s_nop 1
	v_add_f32_dpp v180, v180, v180 row_bcast:31 row_mask:0xc bank_mask:0xf
	s_nop 0
	v_readlane_b32 s20, v180, 63
	s_nop 1
	v_mul_f32_e32 v184, s20, v2
	v_sub_f32_e32 v136, v136, v184
	v_sub_f32_e32 v137, v137, v184
	v_sub_f32_e32 v138, v138, v184
	v_sub_f32_e32 v139, v139, v184
	v_sub_f32_e32 v140, v140, v184
	v_sub_f32_e32 v141, v141, v184
	v_sub_f32_e32 v142, v142, v184
	v_sub_f32_e32 v143, v143, v184
	v_sub_f32_e32 v144, v144, v184
	v_sub_f32_e32 v145, v145, v184
	v_sub_f32_e32 v146, v146, v184
	v_sub_f32_e32 v147, v147, v184
	v_sub_f32_e32 v148, v148, v184
	v_sub_f32_e32 v149, v149, v184
	v_sub_f32_e32 v150, v150, v184
	v_sub_f32_e32 v151, v151, v184
	v_mul_f32_e32 v180, v136, v136
	v_mul_f32_e32 v181, v140, v140
	v_mul_f32_e32 v182, v144, v144
	v_mul_f32_e32 v183, v148, v148
	v_fmac_f32_e32 v180, v137, v137
	v_fmac_f32_e32 v181, v141, v141
	v_fmac_f32_e32 v182, v145, v145
	v_fmac_f32_e32 v183, v149, v149
	v_fmac_f32_e32 v180, v138, v138
	v_fmac_f32_e32 v181, v142, v142
	v_fmac_f32_e32 v182, v146, v146
	v_fmac_f32_e32 v183, v150, v150
	v_fmac_f32_e32 v180, v139, v139
	v_fmac_f32_e32 v181, v143, v143
	v_fmac_f32_e32 v182, v147, v147
	v_fmac_f32_e32 v183, v151, v151
	v_add_f32_e32 v180, v180, v181
	v_add_f32_e32 v182, v182, v183
	v_add_f32_e32 v180, v180, v182
	s_nop 1
	v_add_f32_dpp v180, v180, v180 quad_perm:[1,0,3,2] row_mask:0xf bank_mask:0xf
	s_nop 1
	v_add_f32_dpp v180, v180, v180 quad_perm:[2,3,0,1] row_mask:0xf bank_mask:0xf
	s_nop 1
	v_add_f32_dpp v180, v180, v180 row_half_mirror row_mask:0xf bank_mask:0xf
	s_nop 1
	v_add_f32_dpp v180, v180, v180 row_mirror row_mask:0xf bank_mask:0xf
	s_nop 1
	v_add_f32_dpp v180, v180, v180 row_bcast:15 row_mask:0xa bank_mask:0xf
	s_nop 1
	v_add_f32_dpp v180, v180, v180 row_bcast:31 row_mask:0xc bank_mask:0xf
	s_nop 0
	v_readlane_b32 s20, v180, 63
	s_nop 1
	v_mov_b32_e32 v185, s20
	v_fma_f32 v185, v185, v2, v4
	v_rsq_f32_e32 v185, v185
	s_nop 0
	v_mul_f32_e32 v136, v136, v185
	v_mul_f32_e32 v137, v137, v185
	v_mul_f32_e32 v138, v138, v185
	v_mul_f32_e32 v139, v139, v185
	v_mul_f32_e32 v140, v140, v185
	v_mul_f32_e32 v141, v141, v185
	v_mul_f32_e32 v142, v142, v185
	v_mul_f32_e32 v143, v143, v185
	v_mul_f32_e32 v144, v144, v185
	v_mul_f32_e32 v145, v145, v185
	v_mul_f32_e32 v146, v146, v185
	v_mul_f32_e32 v147, v147, v185
	v_mul_f32_e32 v148, v148, v185
	v_mul_f32_e32 v149, v149, v185
	v_mul_f32_e32 v150, v150, v185
	v_mul_f32_e32 v151, v151, v185
	v_fma_f32 v136, v136, v8, v24
	v_fma_f32 v137, v137, v9, v25
	v_fma_f32 v138, v138, v10, v26
	v_fma_f32 v139, v139, v11, v27
	v_fma_f32 v140, v140, v12, v28
	v_fma_f32 v141, v141, v13, v29
	v_fma_f32 v142, v142, v14, v30
	v_fma_f32 v143, v143, v15, v31
	v_fma_f32 v144, v144, v16, v32
	v_fma_f32 v145, v145, v17, v33
	v_fma_f32 v146, v146, v18, v34
	v_fma_f32 v147, v147, v19, v35
	v_fma_f32 v148, v148, v20, v36
	v_fma_f32 v149, v149, v21, v37
	v_fma_f32 v150, v150, v22, v38
	v_fma_f32 v151, v151, v23, v39
	v_add_u32_e32 v171, 0x6000, v1
	global_store_dwordx4 v171, v[136:139], s[4:5]
	global_store_dwordx4 v171, v[140:143], s[4:5] offset:1024
	global_store_dwordx4 v171, v[144:147], s[4:5] offset:2048
	global_store_dwordx4 v171, v[148:151], s[4:5] offset:3072
	s_waitcnt vmcnt(28)
	v_add_f32_e32 v180, v152, v153
	v_add_f32_e32 v181, v156, v157
	v_add_f32_e32 v182, v160, v161
	v_add_f32_e32 v183, v164, v165
	v_add_f32_e32 v180, v180, v154
	v_add_f32_e32 v181, v181, v158
	v_add_f32_e32 v182, v182, v162
	v_add_f32_e32 v183, v183, v166
	v_add_f32_e32 v180, v180, v155
	v_add_f32_e32 v181, v181, v159
	v_add_f32_e32 v182, v182, v163
	v_add_f32_e32 v183, v183, v167
	v_add_f32_e32 v180, v180, v181
	v_add_f32_e32 v182, v182, v183
	v_add_f32_e32 v180, v180, v182
	s_nop 1
	v_add_f32_dpp v180, v180, v180 quad_perm:[1,0,3,2] row_mask:0xf bank_mask:0xf
	s_nop 1
	v_add_f32_dpp v180, v180, v180 quad_perm:[2,3,0,1] row_mask:0xf bank_mask:0xf
	s_nop 1
	v_add_f32_dpp v180, v180, v180 row_half_mirror row_mask:0xf bank_mask:0xf
	s_nop 1
	v_add_f32_dpp v180, v180, v180 row_mirror row_mask:0xf bank_mask:0xf
	s_nop 1
	v_add_f32_dpp v180, v180, v180 row_bcast:15 row_mask:0xa bank_mask:0xf
	s_nop 1
	v_add_f32_dpp v180, v180, v180 row_bcast:31 row_mask:0xc bank_mask:0xf
	s_nop 0
	v_readlane_b32 s20, v180, 63
	s_nop 1
	v_mul_f32_e32 v184, s20, v2
	v_sub_f32_e32 v152, v152, v184
	v_sub_f32_e32 v153, v153, v184
	v_sub_f32_e32 v154, v154, v184
	v_sub_f32_e32 v155, v155, v184
	v_sub_f32_e32 v156, v156, v184
	v_sub_f32_e32 v157, v157, v184
	v_sub_f32_e32 v158, v158, v184
	v_sub_f32_e32 v159, v159, v184
	v_sub_f32_e32 v160, v160, v184
	v_sub_f32_e32 v161, v161, v184
	v_sub_f32_e32 v162, v162, v184
	v_sub_f32_e32 v163, v163, v184
	v_sub_f32_e32 v164, v164, v184
	v_sub_f32_e32 v165, v165, v184
	v_sub_f32_e32 v166, v166, v184
	v_sub_f32_e32 v167, v167, v184
	v_mul_f32_e32 v180, v152, v152
	v_mul_f32_e32 v181, v156, v156
	v_mul_f32_e32 v182, v160, v160
	v_mul_f32_e32 v183, v164, v164
	v_fmac_f32_e32 v180, v153, v153
	v_fmac_f32_e32 v181, v157, v157
	v_fmac_f32_e32 v182, v161, v161
	v_fmac_f32_e32 v183, v165, v165
	v_fmac_f32_e32 v180, v154, v154
	v_fmac_f32_e32 v181, v158, v158
	v_fmac_f32_e32 v182, v162, v162
	v_fmac_f32_e32 v183, v166, v166
	v_fmac_f32_e32 v180, v155, v155
	v_fmac_f32_e32 v181, v159, v159
	v_fmac_f32_e32 v182, v163, v163
	v_fmac_f32_e32 v183, v167, v167
	v_add_f32_e32 v180, v180, v181
	v_add_f32_e32 v182, v182, v183
	v_add_f32_e32 v180, v180, v182
	s_nop 1
	v_add_f32_dpp v180, v180, v180 quad_perm:[1,0,3,2] row_mask:0xf bank_mask:0xf
	s_nop 1
	v_add_f32_dpp v180, v180, v180 quad_perm:[2,3,0,1] row_mask:0xf bank_mask:0xf
	s_nop 1
	v_add_f32_dpp v180, v180, v180 row_half_mirror row_mask:0xf bank_mask:0xf
	s_nop 1
	v_add_f32_dpp v180, v180, v180 row_mirror row_mask:0xf bank_mask:0xf
	s_nop 1
	v_add_f32_dpp v180, v180, v180 row_bcast:15 row_mask:0xa bank_mask:0xf
	s_nop 1
	v_add_f32_dpp v180, v180, v180 row_bcast:31 row_mask:0xc bank_mask:0xf
	s_nop 0
	v_readlane_b32 s20, v180, 63
	s_nop 1
	v_mov_b32_e32 v185, s20
	v_fma_f32 v185, v185, v2, v4
	v_rsq_f32_e32 v185, v185
	s_nop 0
	v_mul_f32_e32 v152, v152, v185
	v_mul_f32_e32 v153, v153, v185
	v_mul_f32_e32 v154, v154, v185
	v_mul_f32_e32 v155, v155, v185
	v_mul_f32_e32 v156, v156, v185
	v_mul_f32_e32 v157, v157, v185
	v_mul_f32_e32 v158, v158, v185
	v_mul_f32_e32 v159, v159, v185
	v_mul_f32_e32 v160, v160, v185
	v_mul_f32_e32 v161, v161, v185
	v_mul_f32_e32 v162, v162, v185
	v_mul_f32_e32 v163, v163, v185
	v_mul_f32_e32 v164, v164, v185
	v_mul_f32_e32 v165, v165, v185
	v_mul_f32_e32 v166, v166, v185
	v_mul_f32_e32 v167, v167, v185
	v_fma_f32 v152, v152, v8, v24
	v_fma_f32 v153, v153, v9, v25
	v_fma_f32 v154, v154, v10, v26
	v_fma_f32 v155, v155, v11, v27
	v_fma_f32 v156, v156, v12, v28
	v_fma_f32 v157, v157, v13, v29
	v_fma_f32 v158, v158, v14, v30
	v_fma_f32 v159, v159, v15, v31
	v_fma_f32 v160, v160, v16, v32
	v_fma_f32 v161, v161, v17, v33
	v_fma_f32 v162, v162, v18, v34
	v_fma_f32 v163, v163, v19, v35
	v_fma_f32 v164, v164, v20, v36
	v_fma_f32 v165, v165, v21, v37
	v_fma_f32 v166, v166, v22, v38
	v_fma_f32 v167, v167, v23, v39
	v_add_u32_e32 v171, 0x7000, v1
	global_store_dwordx4 v171, v[152:155], s[4:5]
	global_store_dwordx4 v171, v[156:159], s[4:5] offset:1024
	global_store_dwordx4 v171, v[160:163], s[4:5] offset:2048
	global_store_dwordx4 v171, v[164:167], s[4:5] offset:3072
	s_branch .Ltr_29
